# v25 + batched kind-5/7 epilogue too; all 8 epilogue kinds hand-written, the compiler's unreachable 8.9k-line epilogue deleted and the new blocks placed inline
# speedup vs baseline: 1.0205x; 1.0003x over previous
; #define PG8_STAGE(bufoff, gbase, voff) do { _Pragma("unroll") for (int _i = 0; _i < 2; ++_i) \
;     __builtin_amdgcn_global_load_lds((const unsigned*)((const char*)(gbase) + (voff)[_i]), (LAS unsigned*)(lds + (bufoff) + ldsw + _i * 8192), 16, 0, 0); } while (0)
; #define PG8_LDA(dst, b, h) do { _Pragma("unroll") for (int m = 0; m < 4; ++m) _Pragma("unroll") for (int k = 0; k < 2; ++k) dst[m][k] = *(const LAS bf16x8*)(lds + PG8_SA(b, h) + aoff + m * 2048 + k * 1024); } while (0)
; #define PG8_LDB(dst, b, h) do { _Pragma("unroll") for (int n = 0; n < 2; ++n) _Pragma("unroll") for (int k = 0; k < 2; ++k) dst[n][k] = *(const LAS bf16x8*)(lds + PG8_SB(b, h) + boff + n * 2048 + k * 1024); } while (0)
; #define PG8_MMA(ai, bj, At, Bt) do { __builtin_amdgcn_s_setprio(1); _Pragma("unroll") for (int m = 0; m < 4; ++m) _Pragma("unroll") for (int n = 0; n < 2; ++n) _Pragma("unroll") for (int k = 0; k < 2; ++k) \
;     acc[ai][bj][m][n] = __builtin_amdgcn_mfma_f32_16x16x32_bf16(Bt[n][k], At[m][k], acc[ai][bj][m][n], 0, 0, 0); __builtin_amdgcn_s_setprio(0); } while (0)
; #define PG8_WAIT_L(n) asm volatile("s_waitcnt lgkmcnt(" #n ")" ::: "memory")
; #define PG8_BAR __builtin_amdgcn_s_barrier()
; #define PG8_SCHED __builtin_amdgcn_sched_barrier(0)
; template <class Epi>
; __device__ __forceinline__ void gemm_phase(LAS unsigned char* lds, const Gemm g, const Epi& E) {
;     ...
;     for (int t = 0; t < nt; t += 2) {
;       const bool last = (t == nt - 2);
;       const char* a1 = cA + (size_t)(t + 1) * kstep;
;       const char* a2 = last ? nA : cA + (size_t)(t + 2) * kstep; const char* b2 = last ? nB : cB + (size_t)(t + 2) * kstep;
;       const char* a3 = a2 + kstep; const char* b3 = b2 + kstep;
;       PG8_LDB(B0, 0, 0); PG8_SCHED; PG8_LDA(At, 0, 0); PG8_STAGE(PG8_SA(1, 1), a1 + hstepA, voffA);
;       PG8_WAIT_L(8); PG8_BAR; PG8_WAIT_L(0); PG8_MMA(0, 0, At, B0); PG8_BAR; PG8_SCHED;
;       PG8_LDB(B1, 0, 1); PG8_STAGE(PG8_SB(0, 0), b2, voffB);
;       PG8_BAR; PG8_WAIT_L(0); PG8_MMA(0, 1, At, B1); PG8_BAR;
;       PG8_LDA(At, 0, 1); PG8_STAGE(PG8_SA(0, 0), a2, voffA);
;       PG8_BAR; PG8_WAIT_L(0); PG8_MMA(1, 0, At, B0); PG8_BAR; PG8_SCHED;
.LBB0_579:
	s_add_i32 s76, s26, 2
	s_add_u32 s28, s2, 0x80
	s_addc_u32 s27, s3, 0
	s_add_i32 s83, 0, 0x10000
	v_add_u32_e32 v156, s83, v173
	ds_read_b128 v[128:131], v156
	ds_read_b128 v[148:151], v156 offset:1024
	ds_read_b128 v[152:155], v156 offset:2048
	ds_read_b128 v[156:159], v156 offset:3072
	s_cmp_eq_u32 s89, s26
	s_cselect_b32 s26, s0, s28
	s_cselect_b32 s27, s1, s27
	s_cselect_b32 s29, s21, s39
	s_cselect_b32 s28, s20, s38
	v_lshl_add_u64 v[196:197], s[2:3], 0, v[144:145]
	s_add_i32 m0, s84, 0xc000
	ds_read_b128 v[160:163], v175
	ds_read_b128 v[164:167], v175 offset:1024
	ds_read_b128 v[168:171], v175 offset:2048
	ds_read_b128 v[176:179], v175 offset:3072
	ds_read_b128 v[180:183], v175 offset:4096
	ds_read_b128 v[184:187], v175 offset:5120
	ds_read_b128 v[188:191], v175 offset:6144
	ds_read_b128 v[192:195], v175 offset:7168
	global_load_lds_dwordx4 v[196:197], off
	v_lshl_add_u64 v[196:197], s[2:3], 0, v[146:147]
	s_add_i32 m0, s84, 0xe000
	s_nop 0
	global_load_lds_dwordx4 v[196:197], off
	s_waitcnt lgkmcnt(8)
	s_barrier
	s_waitcnt lgkmcnt(0)
	s_setprio 1
	s_waitcnt lgkmcnt(0)
	v_mfma_f32_16x16x32_bf16 v[124:127], v[128:131], v[160:163], v[124:127]
	v_mfma_f32_16x16x32_bf16 v[120:123], v[152:155], v[160:163], v[120:123]
	v_mfma_f32_16x16x32_bf16 v[108:111], v[128:131], v[168:171], v[108:111]
	v_mfma_f32_16x16x32_bf16 v[104:107], v[152:155], v[168:171], v[104:107]
	v_mfma_f32_16x16x32_bf16 v[92:95], v[128:131], v[180:183], v[92:95]
	v_mfma_f32_16x16x32_bf16 v[88:91], v[152:155], v[180:183], v[88:91]
	v_mfma_f32_16x16x32_bf16 v[76:79], v[128:131], v[188:191], v[76:79]
	v_mfma_f32_16x16x32_bf16 v[72:75], v[152:155], v[188:191], v[72:75]
	v_mfma_f32_16x16x32_bf16 v[124:127], v[148:151], v[164:167], v[124:127]
	v_mfma_f32_16x16x32_bf16 v[120:123], v[156:159], v[164:167], v[120:123]
	v_mfma_f32_16x16x32_bf16 v[108:111], v[148:151], v[176:179], v[108:111]
	v_mfma_f32_16x16x32_bf16 v[104:107], v[156:159], v[176:179], v[104:107]
	v_mfma_f32_16x16x32_bf16 v[92:95], v[148:151], v[184:187], v[92:95]
	v_mfma_f32_16x16x32_bf16 v[88:91], v[156:159], v[184:187], v[88:91]
	v_mfma_f32_16x16x32_bf16 v[76:79], v[148:151], v[192:195], v[76:79]
	v_mfma_f32_16x16x32_bf16 v[72:75], v[156:159], v[192:195], v[72:75]
	s_setprio 0
	s_barrier
	s_add_i32 s94, 0, 0x14000
	s_add_i32 s83, s83, s97
	v_add_u32_e32 v208, s94, v173
	v_lshl_add_u64 v[212:213], s[28:29], 0, v[132:133]
	s_mov_b32 m0, s83
	ds_read_b128 v[196:199], v208
	ds_read_b128 v[200:203], v208 offset:1024
	ds_read_b128 v[204:207], v208 offset:2048
	ds_read_b128 v[208:211], v208 offset:3072
	global_load_lds_dwordx4 v[212:213], off
	v_lshl_add_u64 v[214:215], s[28:29], 0, v[142:143]
	s_add_i32 m0, s83, 0x2000
	s_nop 0
	global_load_lds_dwordx4 v[214:215], off
	s_barrier
	s_waitcnt lgkmcnt(0)
	s_setprio 1
	s_waitcnt lgkmcnt(0)
	v_mfma_f32_16x16x32_bf16 v[116:119], v[196:199], v[160:163], v[116:119]
	v_mfma_f32_16x16x32_bf16 v[112:115], v[204:207], v[160:163], v[112:115]
	v_mfma_f32_16x16x32_bf16 v[100:103], v[196:199], v[168:171], v[100:103]
	v_mfma_f32_16x16x32_bf16 v[96:99], v[204:207], v[168:171], v[96:99]
	v_mfma_f32_16x16x32_bf16 v[84:87], v[196:199], v[180:183], v[84:87]
	v_mfma_f32_16x16x32_bf16 v[80:83], v[204:207], v[180:183], v[80:83]
	v_mfma_f32_16x16x32_bf16 v[68:71], v[196:199], v[188:191], v[68:71]
	v_mfma_f32_16x16x32_bf16 v[64:67], v[204:207], v[188:191], v[64:67]
	v_mfma_f32_16x16x32_bf16 v[116:119], v[200:203], v[164:167], v[116:119]
	v_mfma_f32_16x16x32_bf16 v[112:115], v[208:211], v[164:167], v[112:115]
	v_mfma_f32_16x16x32_bf16 v[100:103], v[200:203], v[176:179], v[100:103]
	v_mfma_f32_16x16x32_bf16 v[96:99], v[208:211], v[176:179], v[96:99]
	v_mfma_f32_16x16x32_bf16 v[84:87], v[200:203], v[184:187], v[84:87]
	v_mfma_f32_16x16x32_bf16 v[80:83], v[208:211], v[184:187], v[80:83]
	v_mfma_f32_16x16x32_bf16 v[68:71], v[200:203], v[192:195], v[68:71]
	v_mfma_f32_16x16x32_bf16 v[64:67], v[208:211], v[192:195], v[64:67]
	s_setprio 0
	s_mov_b32 m0, s84
	v_lshl_add_u64 v[216:217], s[26:27], 0, v[138:139]
	s_barrier
	ds_read_b128 v[160:163], v175 offset:16384
	ds_read_b128 v[164:167], v175 offset:17408
	ds_read_b128 v[168:171], v175 offset:18432
	ds_read_b128 v[176:179], v175 offset:19456
	ds_read_b128 v[180:183], v175 offset:20480
	ds_read_b128 v[184:187], v175 offset:21504
	ds_read_b128 v[188:191], v175 offset:22528
	ds_read_b128 v[192:195], v175 offset:23552
	global_load_lds_dwordx4 v[216:217], off
	v_lshl_add_u64 v[218:219], s[26:27], 0, v[140:141]
	s_mov_b32 m0, s85
	s_nop 0
	global_load_lds_dwordx4 v[218:219], off
	s_barrier
	s_waitcnt lgkmcnt(0)
	s_setprio 1
	s_waitcnt lgkmcnt(0)
	v_mfma_f32_16x16x32_bf16 v[60:63], v[128:131], v[160:163], v[60:63]
	v_mfma_f32_16x16x32_bf16 v[56:59], v[152:155], v[160:163], v[56:59]
	v_mfma_f32_16x16x32_bf16 v[44:47], v[128:131], v[168:171], v[44:47]
	v_mfma_f32_16x16x32_bf16 v[40:43], v[152:155], v[168:171], v[40:43]
	v_mfma_f32_16x16x32_bf16 v[28:31], v[128:131], v[180:183], v[28:31]
	v_mfma_f32_16x16x32_bf16 v[24:27], v[152:155], v[180:183], v[24:27]
	v_mfma_f32_16x16x32_bf16 v[12:15], v[128:131], v[188:191], v[12:15]
	v_mfma_f32_16x16x32_bf16 v[8:11], v[152:155], v[188:191], v[8:11]
	v_mfma_f32_16x16x32_bf16 v[60:63], v[148:151], v[164:167], v[60:63]
	v_mfma_f32_16x16x32_bf16 v[56:59], v[156:159], v[164:167], v[56:59]
	v_mfma_f32_16x16x32_bf16 v[44:47], v[148:151], v[176:179], v[44:47]
	v_mfma_f32_16x16x32_bf16 v[40:43], v[156:159], v[176:179], v[40:43]
	v_mfma_f32_16x16x32_bf16 v[28:31], v[148:151], v[184:187], v[28:31]
	v_mfma_f32_16x16x32_bf16 v[24:27], v[156:159], v[184:187], v[24:27]
	v_mfma_f32_16x16x32_bf16 v[12:15], v[148:151], v[192:195], v[12:15]
	v_mfma_f32_16x16x32_bf16 v[8:11], v[156:159], v[192:195], v[8:11]
	s_setprio 0
	s_barrier
; #define PG8_STAGE(bufoff, gbase, voff) do { _Pragma("unroll") for (int _i = 0; _i < 2; ++_i) \
;     __builtin_amdgcn_global_load_lds((const unsigned*)((const char*)(gbase) + (voff)[_i]), (LAS unsigned*)(lds + (bufoff) + ldsw + _i * 8192), 16, 0, 0); } while (0)
; #define PG8_LDA(dst, b, h) do { _Pragma("unroll") for (int m = 0; m < 4; ++m) _Pragma("unroll") for (int k = 0; k < 2; ++k) dst[m][k] = *(const LAS bf16x8*)(lds + PG8_SA(b, h) + aoff + m * 2048 + k * 1024); } while (0)
; #define PG8_LDB(dst, b, h) do { _Pragma("unroll") for (int n = 0; n < 2; ++n) _Pragma("unroll") for (int k = 0; k < 2; ++k) dst[n][k] = *(const LAS bf16x8*)(lds + PG8_SB(b, h) + boff + n * 2048 + k * 1024); } while (0)
; #define PG8_MMA(ai, bj, At, Bt) do { __builtin_amdgcn_s_setprio(1); _Pragma("unroll") for (int m = 0; m < 4; ++m) _Pragma("unroll") for (int n = 0; n < 2; ++n) _Pragma("unroll") for (int k = 0; k < 2; ++k) \
;     acc[ai][bj][m][n] = __builtin_amdgcn_mfma_f32_16x16x32_bf16(Bt[n][k], At[m][k], acc[ai][bj][m][n], 0, 0, 0); __builtin_amdgcn_s_setprio(0); } while (0)
; #define PG8_WAIT_V(n) asm volatile("s_waitcnt vmcnt(" #n ")" ::: "memory")
; #define PG8_WAIT_L(n) asm volatile("s_waitcnt lgkmcnt(" #n ")" ::: "memory")
; #define PG8_BAR __builtin_amdgcn_s_barrier()
; #define PG8_SCHED __builtin_amdgcn_sched_barrier(0)
; template <class Epi>
; __device__ __forceinline__ void gemm_phase(LAS unsigned char* lds, const Gemm g, const Epi& E) {
;     ...
;       PG8_STAGE(PG8_SB(0, 1), b2 + hstepB, voffB);
;       PG8_WAIT_V(6); PG8_BAR; PG8_MMA(1, 1, At, B1); PG8_BAR;
;       PG8_LDB(B0, 1, 0); PG8_SCHED; PG8_LDA(At, 1, 0); PG8_STAGE(PG8_SA(0, 1), a2 + hstepA, voffA);
;       PG8_WAIT_L(8); PG8_BAR; PG8_WAIT_L(0); PG8_MMA(0, 0, At, B0); PG8_BAR; PG8_SCHED;
;       PG8_LDB(B1, 1, 1); PG8_STAGE(PG8_SB(1, 0), b3, voffB);
	s_add_u32 s28, s28, s95
	s_addc_u32 s29, s29, 0
	s_add_i32 s83, s94, s97
	v_lshl_add_u64 v[220:221], s[28:29], 0, v[132:133]
	s_mov_b32 m0, s83
	v_lshl_add_u64 v[222:223], s[28:29], 0, v[142:143]
	global_load_lds_dwordx4 v[220:221], off
	s_add_i32 m0, s83, 0x2000
	s_nop 0
	global_load_lds_dwordx4 v[222:223], off
	s_waitcnt vmcnt(6)
	s_barrier
	s_setprio 1
	v_mfma_f32_16x16x32_bf16 v[52:55], v[196:199], v[160:163], v[52:55]
	v_mfma_f32_16x16x32_bf16 v[48:51], v[204:207], v[160:163], v[48:51]
	v_mfma_f32_16x16x32_bf16 v[36:39], v[196:199], v[168:171], v[36:39]
	v_mfma_f32_16x16x32_bf16 v[32:35], v[204:207], v[168:171], v[32:35]
	v_mfma_f32_16x16x32_bf16 v[20:23], v[196:199], v[180:183], v[20:23]
	v_mfma_f32_16x16x32_bf16 v[16:19], v[204:207], v[180:183], v[16:19]
	v_mfma_f32_16x16x32_bf16 v[4:7], v[196:199], v[188:191], v[4:7]
	v_mfma_f32_16x16x32_bf16 v[0:3], v[204:207], v[188:191], v[0:3]
	v_mfma_f32_16x16x32_bf16 v[52:55], v[200:203], v[164:167], v[52:55]
	v_mfma_f32_16x16x32_bf16 v[48:51], v[208:211], v[164:167], v[48:51]
	v_mfma_f32_16x16x32_bf16 v[36:39], v[200:203], v[176:179], v[36:39]
	v_mfma_f32_16x16x32_bf16 v[32:35], v[208:211], v[176:179], v[32:35]
	v_mfma_f32_16x16x32_bf16 v[20:23], v[200:203], v[184:187], v[20:23]
	v_mfma_f32_16x16x32_bf16 v[16:19], v[208:211], v[184:187], v[16:19]
	v_mfma_f32_16x16x32_bf16 v[4:7], v[200:203], v[192:195], v[4:7]
	v_mfma_f32_16x16x32_bf16 v[0:3], v[208:211], v[192:195], v[0:3]
	s_setprio 0
	s_add_i32 s28, 0, 0x18000
	v_add_u32_e32 v156, s28, v173
	s_barrier
	ds_read_b128 v[128:131], v156
	ds_read_b128 v[148:151], v156 offset:1024
	ds_read_b128 v[152:155], v156 offset:2048
	ds_read_b128 v[156:159], v156 offset:3072
	s_add_u32 s26, s26, s56
	s_addc_u32 s27, s27, 0
	s_mov_b32 m0, s86
	v_lshl_add_u64 v[196:197], s[26:27], 0, v[138:139]
	ds_read_b128 v[160:163], v175 offset:32768
	ds_read_b128 v[164:167], v175 offset:33792
	ds_read_b128 v[168:171], v175 offset:34816
	ds_read_b128 v[176:179], v175 offset:35840
	ds_read_b128 v[180:183], v175 offset:36864
	ds_read_b128 v[184:187], v175 offset:37888
	ds_read_b128 v[188:191], v175 offset:38912
	ds_read_b128 v[192:195], v175 offset:39936
	global_load_lds_dwordx4 v[196:197], off
	v_lshl_add_u64 v[196:197], s[26:27], 0, v[140:141]
	s_mov_b32 m0, s87
	s_nop 0
	global_load_lds_dwordx4 v[196:197], off
	s_waitcnt lgkmcnt(8)
	s_barrier
	s_waitcnt lgkmcnt(0)
	s_setprio 1
	s_waitcnt lgkmcnt(0)
	v_mfma_f32_16x16x32_bf16 v[124:127], v[128:131], v[160:163], v[124:127]
	v_mfma_f32_16x16x32_bf16 v[120:123], v[152:155], v[160:163], v[120:123]
	v_mfma_f32_16x16x32_bf16 v[108:111], v[128:131], v[168:171], v[108:111]
	v_mfma_f32_16x16x32_bf16 v[104:107], v[152:155], v[168:171], v[104:107]
	v_mfma_f32_16x16x32_bf16 v[92:95], v[128:131], v[180:183], v[92:95]
	v_mfma_f32_16x16x32_bf16 v[88:91], v[152:155], v[180:183], v[88:91]
	v_mfma_f32_16x16x32_bf16 v[76:79], v[128:131], v[188:191], v[76:79]
	v_mfma_f32_16x16x32_bf16 v[72:75], v[152:155], v[188:191], v[72:75]
	v_mfma_f32_16x16x32_bf16 v[124:127], v[148:151], v[164:167], v[124:127]
	v_mfma_f32_16x16x32_bf16 v[120:123], v[156:159], v[164:167], v[120:123]
	v_mfma_f32_16x16x32_bf16 v[108:111], v[148:151], v[176:179], v[108:111]
	v_mfma_f32_16x16x32_bf16 v[104:107], v[156:159], v[176:179], v[104:107]
	v_mfma_f32_16x16x32_bf16 v[92:95], v[148:151], v[184:187], v[92:95]
	v_mfma_f32_16x16x32_bf16 v[88:91], v[156:159], v[184:187], v[88:91]
	v_mfma_f32_16x16x32_bf16 v[76:79], v[148:151], v[192:195], v[76:79]
	v_mfma_f32_16x16x32_bf16 v[72:75], v[156:159], v[192:195], v[72:75]
	s_setprio 0
	s_barrier
	s_add_i32 s26, 0, 0x1c000
	s_add_i32 s27, s28, s97
	v_add_u32_e32 v208, s26, v173
	v_lshl_add_u64 v[212:213], v[212:213], 0, s[22:23]
	s_mov_b32 m0, s27
	ds_read_b128 v[196:199], v208
	ds_read_b128 v[200:203], v208 offset:1024
	ds_read_b128 v[204:207], v208 offset:2048
	ds_read_b128 v[208:211], v208 offset:3072
	global_load_lds_dwordx4 v[212:213], off
	v_lshl_add_u64 v[212:213], v[214:215], 0, s[22:23]
	s_add_i32 m0, s27, 0x2000
	s_nop 0
	global_load_lds_dwordx4 v[212:213], off
	s_barrier
; #define PG8_STAGE(bufoff, gbase, voff) do { _Pragma("unroll") for (int _i = 0; _i < 2; ++_i) \
;     __builtin_amdgcn_global_load_lds((const unsigned*)((const char*)(gbase) + (voff)[_i]), (LAS unsigned*)(lds + (bufoff) + ldsw + _i * 8192), 16, 0, 0); } while (0)
; #define PG8_LDA(dst, b, h) do { _Pragma("unroll") for (int m = 0; m < 4; ++m) _Pragma("unroll") for (int k = 0; k < 2; ++k) dst[m][k] = *(const LAS bf16x8*)(lds + PG8_SA(b, h) + aoff + m * 2048 + k * 1024); } while (0)
; #define PG8_MMA(ai, bj, At, Bt) do { __builtin_amdgcn_s_setprio(1); _Pragma("unroll") for (int m = 0; m < 4; ++m) _Pragma("unroll") for (int n = 0; n < 2; ++n) _Pragma("unroll") for (int k = 0; k < 2; ++k) \
;     acc[ai][bj][m][n] = __builtin_amdgcn_mfma_f32_16x16x32_bf16(Bt[n][k], At[m][k], acc[ai][bj][m][n], 0, 0, 0); __builtin_amdgcn_s_setprio(0); } while (0)
; #define PG8_WAIT_V(n) asm volatile("s_waitcnt vmcnt(" #n ")" ::: "memory")
; #define PG8_WAIT_L(n) asm volatile("s_waitcnt lgkmcnt(" #n ")" ::: "memory")
; #define PG8_BAR __builtin_amdgcn_s_barrier()
; #define PG8_SCHED __builtin_amdgcn_sched_barrier(0)
; template <class Epi>
; __device__ __forceinline__ void gemm_phase(LAS unsigned char* lds, const Gemm g, const Epi& E) {
;     ...
;       PG8_BAR; PG8_WAIT_L(0); PG8_MMA(0, 1, At, B1); PG8_BAR;
;       PG8_LDA(At, 1, 1); PG8_STAGE(PG8_SA(1, 0), a3, voffA);
;       PG8_BAR; PG8_WAIT_L(0); PG8_MMA(1, 0, At, B0); PG8_BAR; PG8_SCHED;
;       PG8_STAGE(PG8_SB(1, 1), b3 + hstepB, voffB);
;       PG8_WAIT_V(6); PG8_BAR; PG8_MMA(1, 1, At, B1); PG8_BAR;
;     }
;     {
; #pragma unroll
;       for (int ai = 0; ai < 2; ++ai)
; #pragma unroll
;         for (int m = 0; m < 4; ++m)
; #pragma unroll
;           for (int bj = 0; bj < 2; ++bj)
;           { E.st2(cur.w, cur.pm * BM + ai * HALF + wr * 64 + m * 16 + fr, cur.pn * BM + bj * HALF + wc * 32 + 8 * fq, acc[ai][bj][m][0], acc[ai][bj][m][1]); if (bj == 1 && (m & 1)) asm volatile("" ::: "memory"); }
	s_waitcnt lgkmcnt(0)
	s_setprio 1
	s_waitcnt lgkmcnt(0)
	v_mfma_f32_16x16x32_bf16 v[116:119], v[196:199], v[160:163], v[116:119]
	v_mfma_f32_16x16x32_bf16 v[112:115], v[204:207], v[160:163], v[112:115]
	v_mfma_f32_16x16x32_bf16 v[100:103], v[196:199], v[168:171], v[100:103]
	v_mfma_f32_16x16x32_bf16 v[96:99], v[204:207], v[168:171], v[96:99]
	v_mfma_f32_16x16x32_bf16 v[84:87], v[196:199], v[180:183], v[84:87]
	v_mfma_f32_16x16x32_bf16 v[80:83], v[204:207], v[180:183], v[80:83]
	v_mfma_f32_16x16x32_bf16 v[68:71], v[196:199], v[188:191], v[68:71]
	v_mfma_f32_16x16x32_bf16 v[64:67], v[204:207], v[188:191], v[64:67]
	v_mfma_f32_16x16x32_bf16 v[116:119], v[200:203], v[164:167], v[116:119]
	v_mfma_f32_16x16x32_bf16 v[112:115], v[208:211], v[164:167], v[112:115]
	v_mfma_f32_16x16x32_bf16 v[100:103], v[200:203], v[176:179], v[100:103]
	v_mfma_f32_16x16x32_bf16 v[96:99], v[208:211], v[176:179], v[96:99]
	v_mfma_f32_16x16x32_bf16 v[84:87], v[200:203], v[184:187], v[84:87]
	v_mfma_f32_16x16x32_bf16 v[80:83], v[208:211], v[184:187], v[80:83]
	v_mfma_f32_16x16x32_bf16 v[68:71], v[200:203], v[192:195], v[68:71]
	v_mfma_f32_16x16x32_bf16 v[64:67], v[208:211], v[192:195], v[64:67]
	s_setprio 0
	s_mov_b32 m0, s74
	v_lshl_add_u64 v[212:213], v[216:217], 0, s[22:23]
	s_barrier
	ds_read_b128 v[160:163], v175 offset:49152
	ds_read_b128 v[164:167], v175 offset:50176
	ds_read_b128 v[168:171], v175 offset:51200
	ds_read_b128 v[176:179], v175 offset:52224
	ds_read_b128 v[180:183], v175 offset:53248
	ds_read_b128 v[184:187], v175 offset:54272
	ds_read_b128 v[188:191], v175 offset:55296
	ds_read_b128 v[192:195], v175 offset:56320
	global_load_lds_dwordx4 v[212:213], off
	v_lshl_add_u64 v[212:213], v[218:219], 0, s[22:23]
	s_mov_b32 m0, s78
	s_nop 0
	global_load_lds_dwordx4 v[212:213], off
	s_barrier
	s_waitcnt lgkmcnt(0)
	s_setprio 1
	s_waitcnt lgkmcnt(0)
	v_mfma_f32_16x16x32_bf16 v[60:63], v[128:131], v[160:163], v[60:63]
	v_mfma_f32_16x16x32_bf16 v[56:59], v[152:155], v[160:163], v[56:59]
	v_mfma_f32_16x16x32_bf16 v[44:47], v[128:131], v[168:171], v[44:47]
	v_mfma_f32_16x16x32_bf16 v[40:43], v[152:155], v[168:171], v[40:43]
	v_mfma_f32_16x16x32_bf16 v[28:31], v[128:131], v[180:183], v[28:31]
	v_mfma_f32_16x16x32_bf16 v[24:27], v[152:155], v[180:183], v[24:27]
	v_mfma_f32_16x16x32_bf16 v[12:15], v[128:131], v[188:191], v[12:15]
	v_mfma_f32_16x16x32_bf16 v[8:11], v[152:155], v[188:191], v[8:11]
	v_mfma_f32_16x16x32_bf16 v[60:63], v[148:151], v[164:167], v[60:63]
	v_mfma_f32_16x16x32_bf16 v[56:59], v[156:159], v[164:167], v[56:59]
	v_mfma_f32_16x16x32_bf16 v[44:47], v[148:151], v[176:179], v[44:47]
	v_mfma_f32_16x16x32_bf16 v[40:43], v[156:159], v[176:179], v[40:43]
	v_mfma_f32_16x16x32_bf16 v[28:31], v[148:151], v[184:187], v[28:31]
	v_mfma_f32_16x16x32_bf16 v[24:27], v[156:159], v[184:187], v[24:27]
	v_mfma_f32_16x16x32_bf16 v[12:15], v[148:151], v[192:195], v[12:15]
	v_mfma_f32_16x16x32_bf16 v[8:11], v[156:159], v[192:195], v[8:11]
	s_setprio 0
	s_barrier
	s_add_i32 s26, s26, s97
	v_lshl_add_u64 v[128:129], v[220:221], 0, s[22:23]
	s_mov_b32 m0, s26
	s_nop 0
	global_load_lds_dwordx4 v[128:129], off
	v_lshl_add_u64 v[128:129], v[222:223], 0, s[22:23]
	s_add_i32 m0, s26, 0x2000
	s_nop 0
	global_load_lds_dwordx4 v[128:129], off
	s_waitcnt vmcnt(6)
	s_barrier
	s_setprio 1
	v_mfma_f32_16x16x32_bf16 v[52:55], v[196:199], v[160:163], v[52:55]
	v_mfma_f32_16x16x32_bf16 v[48:51], v[204:207], v[160:163], v[48:51]
	v_mfma_f32_16x16x32_bf16 v[36:39], v[196:199], v[168:171], v[36:39]
	v_mfma_f32_16x16x32_bf16 v[32:35], v[204:207], v[168:171], v[32:35]
	v_mfma_f32_16x16x32_bf16 v[20:23], v[196:199], v[180:183], v[20:23]
	v_mfma_f32_16x16x32_bf16 v[16:19], v[204:207], v[180:183], v[16:19]
	v_mfma_f32_16x16x32_bf16 v[4:7], v[196:199], v[188:191], v[4:7]
	v_mfma_f32_16x16x32_bf16 v[0:3], v[204:207], v[188:191], v[0:3]
	v_mfma_f32_16x16x32_bf16 v[52:55], v[200:203], v[164:167], v[52:55]
	v_mfma_f32_16x16x32_bf16 v[48:51], v[208:211], v[164:167], v[48:51]
	v_mfma_f32_16x16x32_bf16 v[36:39], v[200:203], v[176:179], v[36:39]
	v_mfma_f32_16x16x32_bf16 v[32:35], v[208:211], v[176:179], v[32:35]
	v_mfma_f32_16x16x32_bf16 v[20:23], v[200:203], v[184:187], v[20:23]
	v_mfma_f32_16x16x32_bf16 v[16:19], v[208:211], v[184:187], v[16:19]
	v_mfma_f32_16x16x32_bf16 v[4:7], v[200:203], v[192:195], v[4:7]
	v_mfma_f32_16x16x32_bf16 v[0:3], v[208:211], v[192:195], v[0:3]
	s_setprio 0
	s_add_u32 s2, s2, 0x100
	s_addc_u32 s3, s3, 0
	s_add_u32 s38, s38, 0x100
	s_addc_u32 s39, s39, 0
	s_cmp_ge_u32 s76, s72
	s_mov_b32 s26, s76
	s_barrier
	s_cbranch_scc0 .LBB0_579
	s_lshl_b32 s28, s53, 8
	v_lshl_add_u32 v150, s75, 8, v172
	s_cmp_eq_u32 s12, 0
	v_ashrrev_i32_e32 v151, 31, v150
	v_mad_i64_i32 v[164:165], s[2:3], v150, s54, 0
	v_mad_i64_i32 v[154:155], s[2:3], v150, s33, 0
	s_cselect_b32 s29, s40, s41
	v_lshlrev_b64 v[162:163], 10, v[150:151]
	v_cmp_gt_i32_e64 s[38:39], s92, v150
	v_lshlrev_b64 v[152:153], 12, v[150:151]
	v_or_b32_e32 v148, s28, v174
	s_cmp_eq_u32 s29, 6
	s_cbranch_scc1 .Lepi6
	s_cmp_eq_u32 s29, 0
	s_cbranch_scc1 .Lepi0
	s_cmp_eq_u32 s29, 3
	s_cbranch_scc1 .Lepi3
	s_cmp_eq_u32 s29, 4
	s_cbranch_scc1 .Lepi4
	s_cmp_eq_u32 s29, 1
	s_cbranch_scc1 .Lepi1
	s_cmp_eq_u32 s29, 2
	s_cbranch_scc1 .Lepi2
	s_cmp_eq_u32 s29, 5
	s_cbranch_scc1 .Lepi5
	s_branch .Lepi7

.Lepi0_done:
	s_branch .LBB0_567
.Lepi3:
	v_mul_u32_u24_e32 v176, 0x1800, v150
	v_lshl_add_u32 v176, v148, 1, v176
	v_add_u32_e32 v176, 0x800, v176
	v_lshlrev_b32_e32 v184, 11, v150
	v_lshl_add_u32 v184, v148, 1, v184
	v_add_u32_e32 v177, 0x18000, v176
	v_add_u32_e32 v185, 0x8000, v184
	v_add_u32_e32 v178, 0x30000, v176
	v_add_u32_e32 v186, 0x10000, v184
	v_add_u32_e32 v179, 0x48000, v176
	v_add_u32_e32 v187, 0x18000, v184
	v_add_u32_e32 v180, 0xc0000, v176
	v_add_u32_e32 v188, 0x40000, v184
	v_add_u32_e32 v181, 0xd8000, v176
	v_add_u32_e32 v189, 0x48000, v184
	v_add_u32_e32 v182, 0xf0000, v176
	v_add_u32_e32 v190, 0x50000, v184
	v_add_u32_e32 v183, 0x108000, v176
	v_add_u32_e32 v191, 0x58000, v184
	global_load_dwordx4 v[192:195], v176, s[64:65]
	global_load_dwordx4 v[200:203], v176, s[64:65] offset:256
	global_load_dwordx4 v[208:211], v177, s[64:65]
	global_load_dwordx4 v[216:219], v177, s[64:65] offset:256
	s_waitcnt vmcnt(3)
	v_lshlrev_b32_e32 v152, 16, v192
	v_and_b32_e32 v153, 0xffff0000, v192
	v_lshlrev_b32_e32 v154, 16, v193
	v_and_b32_e32 v155, 0xffff0000, v193
	v_lshlrev_b32_e32 v156, 16, v194
	v_and_b32_e32 v157, 0xffff0000, v194
	v_lshlrev_b32_e32 v158, 16, v195
	v_and_b32_e32 v159, 0xffff0000, v195
	v_mul_f32_e32 v152, 0xbfb8aa3b, v152
	v_mul_f32_e32 v153, 0xbfb8aa3b, v153
	v_mul_f32_e32 v154, 0xbfb8aa3b, v154
	v_mul_f32_e32 v155, 0xbfb8aa3b, v155
	v_mul_f32_e32 v156, 0xbfb8aa3b, v156
	v_mul_f32_e32 v157, 0xbfb8aa3b, v157
	v_mul_f32_e32 v158, 0xbfb8aa3b, v158
	v_mul_f32_e32 v159, 0xbfb8aa3b, v159
	v_exp_f32_e32 v152, v152
	v_exp_f32_e32 v153, v153
	v_exp_f32_e32 v154, v154
	v_exp_f32_e32 v155, v155
	v_exp_f32_e32 v156, v156
	v_exp_f32_e32 v157, v157
	v_exp_f32_e32 v158, v158
	v_exp_f32_e32 v159, v159
	v_pk_add_f32 v[152:153], v[152:153], 1.0 op_sel_hi:[1,0]
	v_pk_add_f32 v[154:155], v[154:155], 1.0 op_sel_hi:[1,0]
	v_pk_add_f32 v[156:157], v[156:157], 1.0 op_sel_hi:[1,0]
	v_pk_add_f32 v[158:159], v[158:159], 1.0 op_sel_hi:[1,0]
	v_div_scale_f32 v160, s[2:3], v152, v152, 1.0
	v_rcp_f32_e32 v161, v160
	s_nop 0
	v_fma_f32 v162, -v160, v161, 1.0
	v_fmac_f32_e32 v161, v162, v161
	v_div_scale_f32 v163, vcc, 1.0, v152, 1.0
	v_mul_f32_e32 v164, v163, v161
	v_div_scale_f32 v128, s[2:3], v153, v153, 1.0
	v_fma_f32 v162, -v160, v164, v163
	v_rcp_f32_e32 v129, v128
	v_fmac_f32_e32 v164, v162, v161
	s_nop 0
	v_fma_f32 v160, -v160, v164, v163
	v_fma_f32 v130, -v128, v129, 1.0
	v_div_fmas_f32 v160, v160, v161, v164
	v_fmac_f32_e32 v129, v130, v129
	v_div_fixup_f32 v152, v160, v152, 1.0
	v_div_scale_f32 v131, vcc, 1.0, v153, 1.0
	v_mul_f32_e32 v165, v131, v129
	v_div_scale_f32 v160, s[2:3], v154, v154, 1.0
	v_fma_f32 v130, -v128, v165, v131
	v_rcp_f32_e32 v161, v160
	v_fmac_f32_e32 v165, v130, v129
	s_nop 0
	v_fma_f32 v128, -v128, v165, v131
	v_fma_f32 v162, -v160, v161, 1.0
	v_div_fmas_f32 v128, v128, v129, v165
	v_fmac_f32_e32 v161, v162, v161
	v_div_fixup_f32 v153, v128, v153, 1.0
	v_div_scale_f32 v163, vcc, 1.0, v154, 1.0
	v_mul_f32_e32 v164, v163, v161
	v_div_scale_f32 v128, s[2:3], v155, v155, 1.0
	v_fma_f32 v162, -v160, v164, v163
	v_rcp_f32_e32 v129, v128
	v_fmac_f32_e32 v164, v162, v161
	s_nop 0
	v_fma_f32 v160, -v160, v164, v163
	v_fma_f32 v130, -v128, v129, 1.0
	v_div_fmas_f32 v160, v160, v161, v164
	v_fmac_f32_e32 v129, v130, v129
	v_div_fixup_f32 v154, v160, v154, 1.0
	v_div_scale_f32 v131, vcc, 1.0, v155, 1.0
	v_mul_f32_e32 v165, v131, v129
	v_div_scale_f32 v160, s[2:3], v156, v156, 1.0
	v_fma_f32 v130, -v128, v165, v131
	v_rcp_f32_e32 v161, v160
	v_fmac_f32_e32 v165, v130, v129
	s_nop 0
	v_fma_f32 v128, -v128, v165, v131
	v_fma_f32 v162, -v160, v161, 1.0
	v_div_fmas_f32 v128, v128, v129, v165
	v_fmac_f32_e32 v161, v162, v161
	v_div_fixup_f32 v155, v128, v155, 1.0
	v_div_scale_f32 v163, vcc, 1.0, v156, 1.0
	v_mul_f32_e32 v164, v163, v161
	v_div_scale_f32 v128, s[2:3], v157, v157, 1.0
	v_fma_f32 v162, -v160, v164, v163
	v_rcp_f32_e32 v129, v128
	v_fmac_f32_e32 v164, v162, v161
	s_nop 0
	v_fma_f32 v160, -v160, v164, v163
	v_fma_f32 v130, -v128, v129, 1.0
	v_div_fmas_f32 v160, v160, v161, v164
	v_fmac_f32_e32 v129, v130, v129
	v_div_fixup_f32 v156, v160, v156, 1.0
	v_div_scale_f32 v131, vcc, 1.0, v157, 1.0
	v_mul_f32_e32 v165, v131, v129
	v_div_scale_f32 v160, s[2:3], v158, v158, 1.0
	v_fma_f32 v130, -v128, v165, v131
	v_rcp_f32_e32 v161, v160
	v_fmac_f32_e32 v165, v130, v129
	s_nop 0
	v_fma_f32 v128, -v128, v165, v131
	v_fma_f32 v162, -v160, v161, 1.0
	v_div_fmas_f32 v128, v128, v129, v165
	v_fmac_f32_e32 v161, v162, v161
	v_div_fixup_f32 v157, v128, v157, 1.0
	v_div_scale_f32 v163, vcc, 1.0, v158, 1.0
	v_mul_f32_e32 v164, v163, v161
	v_div_scale_f32 v128, s[2:3], v159, v159, 1.0
	v_fma_f32 v162, -v160, v164, v163
	v_rcp_f32_e32 v129, v128
	v_fmac_f32_e32 v164, v162, v161
	s_nop 0
	v_fma_f32 v160, -v160, v164, v163
	v_fma_f32 v130, -v128, v129, 1.0
	v_div_fmas_f32 v160, v160, v161, v164
	v_fmac_f32_e32 v129, v130, v129
	v_div_fixup_f32 v158, v160, v158, 1.0
	v_div_scale_f32 v131, vcc, 1.0, v159, 1.0
	v_mul_f32_e32 v165, v131, v129
	v_fma_f32 v130, -v128, v165, v131
	v_fmac_f32_e32 v165, v130, v129
	v_fma_f32 v128, -v128, v165, v131
	v_div_fmas_f32 v128, v128, v129, v165
	v_div_fixup_f32 v159, v128, v159, 1.0
	v_pk_mul_f32 v[152:153], v[124:125], v[152:153]
	v_pk_mul_f32 v[154:155], v[126:127], v[154:155]
	v_pk_mul_f32 v[156:157], v[120:121], v[156:157]
	v_pk_mul_f32 v[158:159], v[122:123], v[158:159]
	v_cvt_pk_bf16_f32 v168, v152, v153
	v_cvt_pk_bf16_f32 v169, v154, v155
	v_cvt_pk_bf16_f32 v170, v156, v157
	v_cvt_pk_bf16_f32 v171, v158, v159
	global_store_dwordx4 v184, v[168:171], s[68:69]
	global_load_dwordx4 v[124:127], v178, s[64:65]
	s_waitcnt vmcnt(4)
; __device__ __forceinline__ float sigmoidf_(float x) { return 1.f / (1.f + __expf(-x)); }
	v_lshlrev_b32_e32 v152, 16, v200
	v_and_b32_e32 v153, 0xffff0000, v200
	v_lshlrev_b32_e32 v154, 16, v201
	v_and_b32_e32 v155, 0xffff0000, v201
	v_lshlrev_b32_e32 v156, 16, v202
	v_and_b32_e32 v157, 0xffff0000, v202
	v_lshlrev_b32_e32 v158, 16, v203
	v_and_b32_e32 v159, 0xffff0000, v203
	v_mul_f32_e32 v152, 0xbfb8aa3b, v152
	v_mul_f32_e32 v153, 0xbfb8aa3b, v153
	v_mul_f32_e32 v154, 0xbfb8aa3b, v154
	v_mul_f32_e32 v155, 0xbfb8aa3b, v155
	v_mul_f32_e32 v156, 0xbfb8aa3b, v156
	v_mul_f32_e32 v157, 0xbfb8aa3b, v157
	v_mul_f32_e32 v158, 0xbfb8aa3b, v158
	v_mul_f32_e32 v159, 0xbfb8aa3b, v159
	v_exp_f32_e32 v152, v152
	v_exp_f32_e32 v153, v153
	v_exp_f32_e32 v154, v154
	v_exp_f32_e32 v155, v155
	v_exp_f32_e32 v156, v156
	v_exp_f32_e32 v157, v157
	v_exp_f32_e32 v158, v158
	v_exp_f32_e32 v159, v159
	v_pk_add_f32 v[152:153], v[152:153], 1.0 op_sel_hi:[1,0]
	v_pk_add_f32 v[154:155], v[154:155], 1.0 op_sel_hi:[1,0]
	v_pk_add_f32 v[156:157], v[156:157], 1.0 op_sel_hi:[1,0]
	v_pk_add_f32 v[158:159], v[158:159], 1.0 op_sel_hi:[1,0]
	v_div_scale_f32 v160, s[2:3], v152, v152, 1.0
	v_rcp_f32_e32 v161, v160
	s_nop 0
	v_fma_f32 v162, -v160, v161, 1.0
	v_fmac_f32_e32 v161, v162, v161
	v_div_scale_f32 v163, vcc, 1.0, v152, 1.0
	v_mul_f32_e32 v164, v163, v161
	v_div_scale_f32 v128, s[2:3], v153, v153, 1.0
	v_fma_f32 v162, -v160, v164, v163
	v_rcp_f32_e32 v129, v128
	v_fmac_f32_e32 v164, v162, v161
	s_nop 0
	v_fma_f32 v160, -v160, v164, v163
	v_fma_f32 v130, -v128, v129, 1.0
	v_div_fmas_f32 v160, v160, v161, v164
	v_fmac_f32_e32 v129, v130, v129
	v_div_fixup_f32 v152, v160, v152, 1.0
	v_div_scale_f32 v131, vcc, 1.0, v153, 1.0
	v_mul_f32_e32 v165, v131, v129
	v_div_scale_f32 v160, s[2:3], v154, v154, 1.0
	v_fma_f32 v130, -v128, v165, v131
	v_rcp_f32_e32 v161, v160
	v_fmac_f32_e32 v165, v130, v129
	s_nop 0
	v_fma_f32 v128, -v128, v165, v131
	v_fma_f32 v162, -v160, v161, 1.0
	v_div_fmas_f32 v128, v128, v129, v165
	v_fmac_f32_e32 v161, v162, v161
	v_div_fixup_f32 v153, v128, v153, 1.0
	v_div_scale_f32 v163, vcc, 1.0, v154, 1.0
	v_mul_f32_e32 v164, v163, v161
	v_div_scale_f32 v128, s[2:3], v155, v155, 1.0
	v_fma_f32 v162, -v160, v164, v163
	v_rcp_f32_e32 v129, v128
	v_fmac_f32_e32 v164, v162, v161
	s_nop 0
	v_fma_f32 v160, -v160, v164, v163
	v_fma_f32 v130, -v128, v129, 1.0
	v_div_fmas_f32 v160, v160, v161, v164
	v_fmac_f32_e32 v129, v130, v129
	v_div_fixup_f32 v154, v160, v154, 1.0
	v_div_scale_f32 v131, vcc, 1.0, v155, 1.0
	v_mul_f32_e32 v165, v131, v129
	v_div_scale_f32 v160, s[2:3], v156, v156, 1.0
	v_fma_f32 v130, -v128, v165, v131
	v_rcp_f32_e32 v161, v160
	v_fmac_f32_e32 v165, v130, v129
	s_nop 0
	v_fma_f32 v128, -v128, v165, v131
	v_fma_f32 v162, -v160, v161, 1.0
	v_div_fmas_f32 v128, v128, v129, v165
	v_fmac_f32_e32 v161, v162, v161
	v_div_fixup_f32 v155, v128, v155, 1.0
	v_div_scale_f32 v163, vcc, 1.0, v156, 1.0
	v_mul_f32_e32 v164, v163, v161
	v_div_scale_f32 v128, s[2:3], v157, v157, 1.0
	v_fma_f32 v162, -v160, v164, v163
	v_rcp_f32_e32 v129, v128
	v_fmac_f32_e32 v164, v162, v161
	s_nop 0
	v_fma_f32 v160, -v160, v164, v163
	v_fma_f32 v130, -v128, v129, 1.0
	v_div_fmas_f32 v160, v160, v161, v164
	v_fmac_f32_e32 v129, v130, v129
	v_div_fixup_f32 v156, v160, v156, 1.0
	v_div_scale_f32 v131, vcc, 1.0, v157, 1.0
	v_mul_f32_e32 v165, v131, v129
	v_div_scale_f32 v160, s[2:3], v158, v158, 1.0
	v_fma_f32 v130, -v128, v165, v131
	v_rcp_f32_e32 v161, v160
	v_fmac_f32_e32 v165, v130, v129
	s_nop 0
	v_fma_f32 v128, -v128, v165, v131
	v_fma_f32 v162, -v160, v161, 1.0
	v_div_fmas_f32 v128, v128, v129, v165
	v_fmac_f32_e32 v161, v162, v161
	v_div_fixup_f32 v157, v128, v157, 1.0
	v_div_scale_f32 v163, vcc, 1.0, v158, 1.0
	v_mul_f32_e32 v164, v163, v161
	v_div_scale_f32 v128, s[2:3], v159, v159, 1.0
	v_fma_f32 v162, -v160, v164, v163
	v_rcp_f32_e32 v129, v128
	v_fmac_f32_e32 v164, v162, v161
	s_nop 0
	v_fma_f32 v160, -v160, v164, v163
	v_fma_f32 v130, -v128, v129, 1.0
	v_div_fmas_f32 v160, v160, v161, v164
	v_fmac_f32_e32 v129, v130, v129
	v_div_fixup_f32 v158, v160, v158, 1.0
	v_div_scale_f32 v131, vcc, 1.0, v159, 1.0
	v_mul_f32_e32 v165, v131, v129
	v_fma_f32 v130, -v128, v165, v131
	v_fmac_f32_e32 v165, v130, v129
	v_fma_f32 v128, -v128, v165, v131
	v_div_fmas_f32 v128, v128, v129, v165
	v_div_fixup_f32 v159, v128, v159, 1.0
	v_pk_mul_f32 v[152:153], v[116:117], v[152:153]
	v_pk_mul_f32 v[154:155], v[118:119], v[154:155]
	v_pk_mul_f32 v[156:157], v[112:113], v[156:157]
	v_pk_mul_f32 v[158:159], v[114:115], v[158:159]
	v_cvt_pk_bf16_f32 v168, v152, v153
	v_cvt_pk_bf16_f32 v169, v154, v155
	v_cvt_pk_bf16_f32 v170, v156, v157
	v_cvt_pk_bf16_f32 v171, v158, v159
	global_store_dwordx4 v184, v[168:171], s[68:69] offset:256
	global_load_dwordx4 v[116:119], v178, s[64:65] offset:256
	s_waitcnt vmcnt(5)
; __device__ __forceinline__ float sigmoidf_(float x) { return 1.f / (1.f + __expf(-x)); }
	v_lshlrev_b32_e32 v152, 16, v208
	v_and_b32_e32 v153, 0xffff0000, v208
	v_lshlrev_b32_e32 v154, 16, v209
	v_and_b32_e32 v155, 0xffff0000, v209
	v_lshlrev_b32_e32 v156, 16, v210
	v_and_b32_e32 v157, 0xffff0000, v210
	v_lshlrev_b32_e32 v158, 16, v211
	v_and_b32_e32 v159, 0xffff0000, v211
	v_mul_f32_e32 v152, 0xbfb8aa3b, v152
	v_mul_f32_e32 v153, 0xbfb8aa3b, v153
	v_mul_f32_e32 v154, 0xbfb8aa3b, v154
	v_mul_f32_e32 v155, 0xbfb8aa3b, v155
	v_mul_f32_e32 v156, 0xbfb8aa3b, v156
	v_mul_f32_e32 v157, 0xbfb8aa3b, v157
	v_mul_f32_e32 v158, 0xbfb8aa3b, v158
	v_mul_f32_e32 v159, 0xbfb8aa3b, v159
	v_exp_f32_e32 v152, v152
	v_exp_f32_e32 v153, v153
	v_exp_f32_e32 v154, v154
	v_exp_f32_e32 v155, v155
	v_exp_f32_e32 v156, v156
	v_exp_f32_e32 v157, v157
	v_exp_f32_e32 v158, v158
	v_exp_f32_e32 v159, v159
	v_pk_add_f32 v[152:153], v[152:153], 1.0 op_sel_hi:[1,0]
	v_pk_add_f32 v[154:155], v[154:155], 1.0 op_sel_hi:[1,0]
	v_pk_add_f32 v[156:157], v[156:157], 1.0 op_sel_hi:[1,0]
	v_pk_add_f32 v[158:159], v[158:159], 1.0 op_sel_hi:[1,0]
	v_div_scale_f32 v160, s[2:3], v152, v152, 1.0
	v_rcp_f32_e32 v161, v160
	s_nop 0
	v_fma_f32 v162, -v160, v161, 1.0
	v_fmac_f32_e32 v161, v162, v161
	v_div_scale_f32 v163, vcc, 1.0, v152, 1.0
	v_mul_f32_e32 v164, v163, v161
	v_div_scale_f32 v128, s[2:3], v153, v153, 1.0
	v_fma_f32 v162, -v160, v164, v163
	v_rcp_f32_e32 v129, v128
	v_fmac_f32_e32 v164, v162, v161
	s_nop 0
	v_fma_f32 v160, -v160, v164, v163
	v_fma_f32 v130, -v128, v129, 1.0
	v_div_fmas_f32 v160, v160, v161, v164
	v_fmac_f32_e32 v129, v130, v129
	v_div_fixup_f32 v152, v160, v152, 1.0
	v_div_scale_f32 v131, vcc, 1.0, v153, 1.0
	v_mul_f32_e32 v165, v131, v129
	v_div_scale_f32 v160, s[2:3], v154, v154, 1.0
	v_fma_f32 v130, -v128, v165, v131
	v_rcp_f32_e32 v161, v160
	v_fmac_f32_e32 v165, v130, v129
	s_nop 0
	v_fma_f32 v128, -v128, v165, v131
	v_fma_f32 v162, -v160, v161, 1.0
	v_div_fmas_f32 v128, v128, v129, v165
	v_fmac_f32_e32 v161, v162, v161
	v_div_fixup_f32 v153, v128, v153, 1.0
	v_div_scale_f32 v163, vcc, 1.0, v154, 1.0
	v_mul_f32_e32 v164, v163, v161
	v_div_scale_f32 v128, s[2:3], v155, v155, 1.0
	v_fma_f32 v162, -v160, v164, v163
	v_rcp_f32_e32 v129, v128
	v_fmac_f32_e32 v164, v162, v161
	s_nop 0
	v_fma_f32 v160, -v160, v164, v163
	v_fma_f32 v130, -v128, v129, 1.0
	v_div_fmas_f32 v160, v160, v161, v164
	v_fmac_f32_e32 v129, v130, v129
	v_div_fixup_f32 v154, v160, v154, 1.0
	v_div_scale_f32 v131, vcc, 1.0, v155, 1.0
	v_mul_f32_e32 v165, v131, v129
	v_div_scale_f32 v160, s[2:3], v156, v156, 1.0
	v_fma_f32 v130, -v128, v165, v131
	v_rcp_f32_e32 v161, v160
	v_fmac_f32_e32 v165, v130, v129
	s_nop 0
	v_fma_f32 v128, -v128, v165, v131
	v_fma_f32 v162, -v160, v161, 1.0
	v_div_fmas_f32 v128, v128, v129, v165
	v_fmac_f32_e32 v161, v162, v161
	v_div_fixup_f32 v155, v128, v155, 1.0
	v_div_scale_f32 v163, vcc, 1.0, v156, 1.0
	v_mul_f32_e32 v164, v163, v161
	v_div_scale_f32 v128, s[2:3], v157, v157, 1.0
	v_fma_f32 v162, -v160, v164, v163
	v_rcp_f32_e32 v129, v128
	v_fmac_f32_e32 v164, v162, v161
	s_nop 0
	v_fma_f32 v160, -v160, v164, v163
	v_fma_f32 v130, -v128, v129, 1.0
	v_div_fmas_f32 v160, v160, v161, v164
	v_fmac_f32_e32 v129, v130, v129
	v_div_fixup_f32 v156, v160, v156, 1.0
	v_div_scale_f32 v131, vcc, 1.0, v157, 1.0
	v_mul_f32_e32 v165, v131, v129
	v_div_scale_f32 v160, s[2:3], v158, v158, 1.0
	v_fma_f32 v130, -v128, v165, v131
	v_rcp_f32_e32 v161, v160
	v_fmac_f32_e32 v165, v130, v129
	s_nop 0
	v_fma_f32 v128, -v128, v165, v131
	v_fma_f32 v162, -v160, v161, 1.0
	v_div_fmas_f32 v128, v128, v129, v165
	v_fmac_f32_e32 v161, v162, v161
	v_div_fixup_f32 v157, v128, v157, 1.0
	v_div_scale_f32 v163, vcc, 1.0, v158, 1.0
	v_mul_f32_e32 v164, v163, v161
	v_div_scale_f32 v128, s[2:3], v159, v159, 1.0
	v_fma_f32 v162, -v160, v164, v163
	v_rcp_f32_e32 v129, v128
	v_fmac_f32_e32 v164, v162, v161
	s_nop 0
	v_fma_f32 v160, -v160, v164, v163
	v_fma_f32 v130, -v128, v129, 1.0
	v_div_fmas_f32 v160, v160, v161, v164
	v_fmac_f32_e32 v129, v130, v129
	v_div_fixup_f32 v158, v160, v158, 1.0
	v_div_scale_f32 v131, vcc, 1.0, v159, 1.0
	v_mul_f32_e32 v165, v131, v129
	v_fma_f32 v130, -v128, v165, v131
	v_fmac_f32_e32 v165, v130, v129
	v_fma_f32 v128, -v128, v165, v131
	v_div_fmas_f32 v128, v128, v129, v165
	v_div_fixup_f32 v159, v128, v159, 1.0
	v_pk_mul_f32 v[152:153], v[108:109], v[152:153]
	v_pk_mul_f32 v[154:155], v[110:111], v[154:155]
	v_pk_mul_f32 v[156:157], v[104:105], v[156:157]
	v_pk_mul_f32 v[158:159], v[106:107], v[158:159]
	v_cvt_pk_bf16_f32 v168, v152, v153
	v_cvt_pk_bf16_f32 v169, v154, v155
	v_cvt_pk_bf16_f32 v170, v156, v157
	v_cvt_pk_bf16_f32 v171, v158, v159
	global_store_dwordx4 v185, v[168:171], s[68:69]
	global_load_dwordx4 v[108:111], v179, s[64:65]
	s_waitcnt vmcnt(6)
; __device__ __forceinline__ float sigmoidf_(float x) { return 1.f / (1.f + __expf(-x)); }
	v_lshlrev_b32_e32 v152, 16, v216
	v_and_b32_e32 v153, 0xffff0000, v216
	v_lshlrev_b32_e32 v154, 16, v217
	v_and_b32_e32 v155, 0xffff0000, v217
	v_lshlrev_b32_e32 v156, 16, v218
	v_and_b32_e32 v157, 0xffff0000, v218
	v_lshlrev_b32_e32 v158, 16, v219
	v_and_b32_e32 v159, 0xffff0000, v219
	v_mul_f32_e32 v152, 0xbfb8aa3b, v152
	v_mul_f32_e32 v153, 0xbfb8aa3b, v153
	v_mul_f32_e32 v154, 0xbfb8aa3b, v154
	v_mul_f32_e32 v155, 0xbfb8aa3b, v155
	v_mul_f32_e32 v156, 0xbfb8aa3b, v156
	v_mul_f32_e32 v157, 0xbfb8aa3b, v157
	v_mul_f32_e32 v158, 0xbfb8aa3b, v158
	v_mul_f32_e32 v159, 0xbfb8aa3b, v159
	v_exp_f32_e32 v152, v152
	v_exp_f32_e32 v153, v153
	v_exp_f32_e32 v154, v154
	v_exp_f32_e32 v155, v155
	v_exp_f32_e32 v156, v156
	v_exp_f32_e32 v157, v157
	v_exp_f32_e32 v158, v158
	v_exp_f32_e32 v159, v159
	v_pk_add_f32 v[152:153], v[152:153], 1.0 op_sel_hi:[1,0]
	v_pk_add_f32 v[154:155], v[154:155], 1.0 op_sel_hi:[1,0]
	v_pk_add_f32 v[156:157], v[156:157], 1.0 op_sel_hi:[1,0]
	v_pk_add_f32 v[158:159], v[158:159], 1.0 op_sel_hi:[1,0]
	v_div_scale_f32 v160, s[2:3], v152, v152, 1.0
	v_rcp_f32_e32 v161, v160
	s_nop 0
	v_fma_f32 v162, -v160, v161, 1.0
	v_fmac_f32_e32 v161, v162, v161
	v_div_scale_f32 v163, vcc, 1.0, v152, 1.0
	v_mul_f32_e32 v164, v163, v161
	v_div_scale_f32 v128, s[2:3], v153, v153, 1.0
	v_fma_f32 v162, -v160, v164, v163
	v_rcp_f32_e32 v129, v128
	v_fmac_f32_e32 v164, v162, v161
	s_nop 0
	v_fma_f32 v160, -v160, v164, v163
	v_fma_f32 v130, -v128, v129, 1.0
	v_div_fmas_f32 v160, v160, v161, v164
	v_fmac_f32_e32 v129, v130, v129
	v_div_fixup_f32 v152, v160, v152, 1.0
	v_div_scale_f32 v131, vcc, 1.0, v153, 1.0
	v_mul_f32_e32 v165, v131, v129
	v_div_scale_f32 v160, s[2:3], v154, v154, 1.0
	v_fma_f32 v130, -v128, v165, v131
	v_rcp_f32_e32 v161, v160
	v_fmac_f32_e32 v165, v130, v129
	s_nop 0
	v_fma_f32 v128, -v128, v165, v131
	v_fma_f32 v162, -v160, v161, 1.0
	v_div_fmas_f32 v128, v128, v129, v165
	v_fmac_f32_e32 v161, v162, v161
	v_div_fixup_f32 v153, v128, v153, 1.0
	v_div_scale_f32 v163, vcc, 1.0, v154, 1.0
	v_mul_f32_e32 v164, v163, v161
	v_div_scale_f32 v128, s[2:3], v155, v155, 1.0
	v_fma_f32 v162, -v160, v164, v163
	v_rcp_f32_e32 v129, v128
	v_fmac_f32_e32 v164, v162, v161
	s_nop 0
	v_fma_f32 v160, -v160, v164, v163
	v_fma_f32 v130, -v128, v129, 1.0
	v_div_fmas_f32 v160, v160, v161, v164
	v_fmac_f32_e32 v129, v130, v129
	v_div_fixup_f32 v154, v160, v154, 1.0
	v_div_scale_f32 v131, vcc, 1.0, v155, 1.0
	v_mul_f32_e32 v165, v131, v129
	v_div_scale_f32 v160, s[2:3], v156, v156, 1.0
	v_fma_f32 v130, -v128, v165, v131
	v_rcp_f32_e32 v161, v160
	v_fmac_f32_e32 v165, v130, v129
	s_nop 0
	v_fma_f32 v128, -v128, v165, v131
	v_fma_f32 v162, -v160, v161, 1.0
	v_div_fmas_f32 v128, v128, v129, v165
	v_fmac_f32_e32 v161, v162, v161
	v_div_fixup_f32 v155, v128, v155, 1.0
	v_div_scale_f32 v163, vcc, 1.0, v156, 1.0
	v_mul_f32_e32 v164, v163, v161
	v_div_scale_f32 v128, s[2:3], v157, v157, 1.0
	v_fma_f32 v162, -v160, v164, v163
	v_rcp_f32_e32 v129, v128
	v_fmac_f32_e32 v164, v162, v161
	s_nop 0
	v_fma_f32 v160, -v160, v164, v163
	v_fma_f32 v130, -v128, v129, 1.0
	v_div_fmas_f32 v160, v160, v161, v164
	v_fmac_f32_e32 v129, v130, v129
	v_div_fixup_f32 v156, v160, v156, 1.0
	v_div_scale_f32 v131, vcc, 1.0, v157, 1.0
	v_mul_f32_e32 v165, v131, v129
	v_div_scale_f32 v160, s[2:3], v158, v158, 1.0
	v_fma_f32 v130, -v128, v165, v131
	v_rcp_f32_e32 v161, v160
	v_fmac_f32_e32 v165, v130, v129
	s_nop 0
	v_fma_f32 v128, -v128, v165, v131
	v_fma_f32 v162, -v160, v161, 1.0
	v_div_fmas_f32 v128, v128, v129, v165
	v_fmac_f32_e32 v161, v162, v161
	v_div_fixup_f32 v157, v128, v157, 1.0
	v_div_scale_f32 v163, vcc, 1.0, v158, 1.0
	v_mul_f32_e32 v164, v163, v161
	v_div_scale_f32 v128, s[2:3], v159, v159, 1.0
	v_fma_f32 v162, -v160, v164, v163
	v_rcp_f32_e32 v129, v128
	v_fmac_f32_e32 v164, v162, v161
	s_nop 0
	v_fma_f32 v160, -v160, v164, v163
	v_fma_f32 v130, -v128, v129, 1.0
	v_div_fmas_f32 v160, v160, v161, v164
	v_fmac_f32_e32 v129, v130, v129
	v_div_fixup_f32 v158, v160, v158, 1.0
	v_div_scale_f32 v131, vcc, 1.0, v159, 1.0
	v_mul_f32_e32 v165, v131, v129
	v_fma_f32 v130, -v128, v165, v131
	v_fmac_f32_e32 v165, v130, v129
	v_fma_f32 v128, -v128, v165, v131
	v_div_fmas_f32 v128, v128, v129, v165
	v_div_fixup_f32 v159, v128, v159, 1.0
	v_pk_mul_f32 v[152:153], v[100:101], v[152:153]
	v_pk_mul_f32 v[154:155], v[102:103], v[154:155]
	v_pk_mul_f32 v[156:157], v[96:97], v[156:157]
	v_pk_mul_f32 v[158:159], v[98:99], v[158:159]
	v_cvt_pk_bf16_f32 v168, v152, v153
	v_cvt_pk_bf16_f32 v169, v154, v155
	v_cvt_pk_bf16_f32 v170, v156, v157
	v_cvt_pk_bf16_f32 v171, v158, v159
	global_store_dwordx4 v185, v[168:171], s[68:69] offset:256
	global_load_dwordx4 v[100:103], v179, s[64:65] offset:256
	s_waitcnt vmcnt(6)
; __device__ __forceinline__ float sigmoidf_(float x) { return 1.f / (1.f + __expf(-x)); }
	v_lshlrev_b32_e32 v152, 16, v124
	v_and_b32_e32 v153, 0xffff0000, v124
	v_lshlrev_b32_e32 v154, 16, v125
	v_and_b32_e32 v155, 0xffff0000, v125
	v_lshlrev_b32_e32 v156, 16, v126
	v_and_b32_e32 v157, 0xffff0000, v126
	v_lshlrev_b32_e32 v158, 16, v127
	v_and_b32_e32 v159, 0xffff0000, v127
	v_mul_f32_e32 v152, 0xbfb8aa3b, v152
	v_mul_f32_e32 v153, 0xbfb8aa3b, v153
	v_mul_f32_e32 v154, 0xbfb8aa3b, v154
	v_mul_f32_e32 v155, 0xbfb8aa3b, v155
	v_mul_f32_e32 v156, 0xbfb8aa3b, v156
	v_mul_f32_e32 v157, 0xbfb8aa3b, v157
	v_mul_f32_e32 v158, 0xbfb8aa3b, v158
	v_mul_f32_e32 v159, 0xbfb8aa3b, v159
	v_exp_f32_e32 v152, v152
	v_exp_f32_e32 v153, v153
	v_exp_f32_e32 v154, v154
	v_exp_f32_e32 v155, v155
	v_exp_f32_e32 v156, v156
	v_exp_f32_e32 v157, v157
	v_exp_f32_e32 v158, v158
	v_exp_f32_e32 v159, v159
	v_pk_add_f32 v[152:153], v[152:153], 1.0 op_sel_hi:[1,0]
	v_pk_add_f32 v[154:155], v[154:155], 1.0 op_sel_hi:[1,0]
	v_pk_add_f32 v[156:157], v[156:157], 1.0 op_sel_hi:[1,0]
	v_pk_add_f32 v[158:159], v[158:159], 1.0 op_sel_hi:[1,0]
	v_div_scale_f32 v160, s[2:3], v152, v152, 1.0
	v_rcp_f32_e32 v161, v160
	s_nop 0
	v_fma_f32 v162, -v160, v161, 1.0
	v_fmac_f32_e32 v161, v162, v161
	v_div_scale_f32 v163, vcc, 1.0, v152, 1.0
	v_mul_f32_e32 v164, v163, v161
	v_div_scale_f32 v128, s[2:3], v153, v153, 1.0
	v_fma_f32 v162, -v160, v164, v163
	v_rcp_f32_e32 v129, v128
	v_fmac_f32_e32 v164, v162, v161
	s_nop 0
	v_fma_f32 v160, -v160, v164, v163
	v_fma_f32 v130, -v128, v129, 1.0
	v_div_fmas_f32 v160, v160, v161, v164
	v_fmac_f32_e32 v129, v130, v129
	v_div_fixup_f32 v152, v160, v152, 1.0
	v_div_scale_f32 v131, vcc, 1.0, v153, 1.0
	v_mul_f32_e32 v165, v131, v129
	v_div_scale_f32 v160, s[2:3], v154, v154, 1.0
	v_fma_f32 v130, -v128, v165, v131
	v_rcp_f32_e32 v161, v160
	v_fmac_f32_e32 v165, v130, v129
	s_nop 0
	v_fma_f32 v128, -v128, v165, v131
	v_fma_f32 v162, -v160, v161, 1.0
	v_div_fmas_f32 v128, v128, v129, v165
	v_fmac_f32_e32 v161, v162, v161
	v_div_fixup_f32 v153, v128, v153, 1.0
	v_div_scale_f32 v163, vcc, 1.0, v154, 1.0
	v_mul_f32_e32 v164, v163, v161
	v_div_scale_f32 v128, s[2:3], v155, v155, 1.0
	v_fma_f32 v162, -v160, v164, v163
	v_rcp_f32_e32 v129, v128
	v_fmac_f32_e32 v164, v162, v161
	s_nop 0
	v_fma_f32 v160, -v160, v164, v163
	v_fma_f32 v130, -v128, v129, 1.0
	v_div_fmas_f32 v160, v160, v161, v164
	v_fmac_f32_e32 v129, v130, v129
	v_div_fixup_f32 v154, v160, v154, 1.0
	v_div_scale_f32 v131, vcc, 1.0, v155, 1.0
	v_mul_f32_e32 v165, v131, v129
	v_div_scale_f32 v160, s[2:3], v156, v156, 1.0
	v_fma_f32 v130, -v128, v165, v131
	v_rcp_f32_e32 v161, v160
	v_fmac_f32_e32 v165, v130, v129
	s_nop 0
	v_fma_f32 v128, -v128, v165, v131
	v_fma_f32 v162, -v160, v161, 1.0
	v_div_fmas_f32 v128, v128, v129, v165
	v_fmac_f32_e32 v161, v162, v161
	v_div_fixup_f32 v155, v128, v155, 1.0
	v_div_scale_f32 v163, vcc, 1.0, v156, 1.0
	v_mul_f32_e32 v164, v163, v161
	v_div_scale_f32 v128, s[2:3], v157, v157, 1.0
	v_fma_f32 v162, -v160, v164, v163
	v_rcp_f32_e32 v129, v128
	v_fmac_f32_e32 v164, v162, v161
	s_nop 0
	v_fma_f32 v160, -v160, v164, v163
	v_fma_f32 v130, -v128, v129, 1.0
	v_div_fmas_f32 v160, v160, v161, v164
	v_fmac_f32_e32 v129, v130, v129
	v_div_fixup_f32 v156, v160, v156, 1.0
	v_div_scale_f32 v131, vcc, 1.0, v157, 1.0
	v_mul_f32_e32 v165, v131, v129
	v_div_scale_f32 v160, s[2:3], v158, v158, 1.0
	v_fma_f32 v130, -v128, v165, v131
	v_rcp_f32_e32 v161, v160
	v_fmac_f32_e32 v165, v130, v129
	s_nop 0
	v_fma_f32 v128, -v128, v165, v131
	v_fma_f32 v162, -v160, v161, 1.0
	v_div_fmas_f32 v128, v128, v129, v165
	v_fmac_f32_e32 v161, v162, v161
	v_div_fixup_f32 v157, v128, v157, 1.0
	v_div_scale_f32 v163, vcc, 1.0, v158, 1.0
	v_mul_f32_e32 v164, v163, v161
	v_div_scale_f32 v128, s[2:3], v159, v159, 1.0
	v_fma_f32 v162, -v160, v164, v163
	v_rcp_f32_e32 v129, v128
	v_fmac_f32_e32 v164, v162, v161
	s_nop 0
	v_fma_f32 v160, -v160, v164, v163
	v_fma_f32 v130, -v128, v129, 1.0
	v_div_fmas_f32 v160, v160, v161, v164
	v_fmac_f32_e32 v129, v130, v129
	v_div_fixup_f32 v158, v160, v158, 1.0
	v_div_scale_f32 v131, vcc, 1.0, v159, 1.0
	v_mul_f32_e32 v165, v131, v129
	v_fma_f32 v130, -v128, v165, v131
	v_fmac_f32_e32 v165, v130, v129
	v_fma_f32 v128, -v128, v165, v131
	v_div_fmas_f32 v128, v128, v129, v165
	v_div_fixup_f32 v159, v128, v159, 1.0
	v_pk_mul_f32 v[152:153], v[92:93], v[152:153]
	v_pk_mul_f32 v[154:155], v[94:95], v[154:155]
	v_pk_mul_f32 v[156:157], v[88:89], v[156:157]
	v_pk_mul_f32 v[158:159], v[90:91], v[158:159]
	v_cvt_pk_bf16_f32 v168, v152, v153
	v_cvt_pk_bf16_f32 v169, v154, v155
	v_cvt_pk_bf16_f32 v170, v156, v157
	v_cvt_pk_bf16_f32 v171, v158, v159
	global_store_dwordx4 v186, v[168:171], s[68:69]
	global_load_dwordx4 v[92:95], v180, s[64:65]
	s_waitcnt vmcnt(6)
; __device__ __forceinline__ float sigmoidf_(float x) { return 1.f / (1.f + __expf(-x)); }
	v_lshlrev_b32_e32 v152, 16, v116
	v_and_b32_e32 v153, 0xffff0000, v116
	v_lshlrev_b32_e32 v154, 16, v117
	v_and_b32_e32 v155, 0xffff0000, v117
	v_lshlrev_b32_e32 v156, 16, v118
	v_and_b32_e32 v157, 0xffff0000, v118
	v_lshlrev_b32_e32 v158, 16, v119
	v_and_b32_e32 v159, 0xffff0000, v119
	v_mul_f32_e32 v152, 0xbfb8aa3b, v152
	v_mul_f32_e32 v153, 0xbfb8aa3b, v153
	v_mul_f32_e32 v154, 0xbfb8aa3b, v154
	v_mul_f32_e32 v155, 0xbfb8aa3b, v155
	v_mul_f32_e32 v156, 0xbfb8aa3b, v156
	v_mul_f32_e32 v157, 0xbfb8aa3b, v157
	v_mul_f32_e32 v158, 0xbfb8aa3b, v158
	v_mul_f32_e32 v159, 0xbfb8aa3b, v159
	v_exp_f32_e32 v152, v152
	v_exp_f32_e32 v153, v153
	v_exp_f32_e32 v154, v154
	v_exp_f32_e32 v155, v155
	v_exp_f32_e32 v156, v156
	v_exp_f32_e32 v157, v157
	v_exp_f32_e32 v158, v158
	v_exp_f32_e32 v159, v159
	v_pk_add_f32 v[152:153], v[152:153], 1.0 op_sel_hi:[1,0]
	v_pk_add_f32 v[154:155], v[154:155], 1.0 op_sel_hi:[1,0]
	v_pk_add_f32 v[156:157], v[156:157], 1.0 op_sel_hi:[1,0]
	v_pk_add_f32 v[158:159], v[158:159], 1.0 op_sel_hi:[1,0]
	v_div_scale_f32 v160, s[2:3], v152, v152, 1.0
	v_rcp_f32_e32 v161, v160
	s_nop 0
	v_fma_f32 v162, -v160, v161, 1.0
	v_fmac_f32_e32 v161, v162, v161
	v_div_scale_f32 v163, vcc, 1.0, v152, 1.0
	v_mul_f32_e32 v164, v163, v161
	v_div_scale_f32 v128, s[2:3], v153, v153, 1.0
	v_fma_f32 v162, -v160, v164, v163
	v_rcp_f32_e32 v129, v128
	v_fmac_f32_e32 v164, v162, v161
	s_nop 0
	v_fma_f32 v160, -v160, v164, v163
	v_fma_f32 v130, -v128, v129, 1.0
	v_div_fmas_f32 v160, v160, v161, v164
	v_fmac_f32_e32 v129, v130, v129
	v_div_fixup_f32 v152, v160, v152, 1.0
	v_div_scale_f32 v131, vcc, 1.0, v153, 1.0
	v_mul_f32_e32 v165, v131, v129
	v_div_scale_f32 v160, s[2:3], v154, v154, 1.0
	v_fma_f32 v130, -v128, v165, v131
	v_rcp_f32_e32 v161, v160
	v_fmac_f32_e32 v165, v130, v129
	s_nop 0
	v_fma_f32 v128, -v128, v165, v131
	v_fma_f32 v162, -v160, v161, 1.0
	v_div_fmas_f32 v128, v128, v129, v165
	v_fmac_f32_e32 v161, v162, v161
	v_div_fixup_f32 v153, v128, v153, 1.0
	v_div_scale_f32 v163, vcc, 1.0, v154, 1.0
	v_mul_f32_e32 v164, v163, v161
	v_div_scale_f32 v128, s[2:3], v155, v155, 1.0
	v_fma_f32 v162, -v160, v164, v163
	v_rcp_f32_e32 v129, v128
	v_fmac_f32_e32 v164, v162, v161
	s_nop 0
	v_fma_f32 v160, -v160, v164, v163
	v_fma_f32 v130, -v128, v129, 1.0
	v_div_fmas_f32 v160, v160, v161, v164
	v_fmac_f32_e32 v129, v130, v129
	v_div_fixup_f32 v154, v160, v154, 1.0
	v_div_scale_f32 v131, vcc, 1.0, v155, 1.0
	v_mul_f32_e32 v165, v131, v129
	v_div_scale_f32 v160, s[2:3], v156, v156, 1.0
	v_fma_f32 v130, -v128, v165, v131
	v_rcp_f32_e32 v161, v160
	v_fmac_f32_e32 v165, v130, v129
	s_nop 0
	v_fma_f32 v128, -v128, v165, v131
	v_fma_f32 v162, -v160, v161, 1.0
	v_div_fmas_f32 v128, v128, v129, v165
	v_fmac_f32_e32 v161, v162, v161
	v_div_fixup_f32 v155, v128, v155, 1.0
	v_div_scale_f32 v163, vcc, 1.0, v156, 1.0
	v_mul_f32_e32 v164, v163, v161
	v_div_scale_f32 v128, s[2:3], v157, v157, 1.0
	v_fma_f32 v162, -v160, v164, v163
	v_rcp_f32_e32 v129, v128
	v_fmac_f32_e32 v164, v162, v161
	s_nop 0
	v_fma_f32 v160, -v160, v164, v163
	v_fma_f32 v130, -v128, v129, 1.0
	v_div_fmas_f32 v160, v160, v161, v164
	v_fmac_f32_e32 v129, v130, v129
	v_div_fixup_f32 v156, v160, v156, 1.0
	v_div_scale_f32 v131, vcc, 1.0, v157, 1.0
	v_mul_f32_e32 v165, v131, v129
	v_div_scale_f32 v160, s[2:3], v158, v158, 1.0
	v_fma_f32 v130, -v128, v165, v131
	v_rcp_f32_e32 v161, v160
	v_fmac_f32_e32 v165, v130, v129
	s_nop 0
	v_fma_f32 v128, -v128, v165, v131
	v_fma_f32 v162, -v160, v161, 1.0
	v_div_fmas_f32 v128, v128, v129, v165
	v_fmac_f32_e32 v161, v162, v161
	v_div_fixup_f32 v157, v128, v157, 1.0
	v_div_scale_f32 v163, vcc, 1.0, v158, 1.0
	v_mul_f32_e32 v164, v163, v161
	v_div_scale_f32 v128, s[2:3], v159, v159, 1.0
	v_fma_f32 v162, -v160, v164, v163
	v_rcp_f32_e32 v129, v128
	v_fmac_f32_e32 v164, v162, v161
	s_nop 0
	v_fma_f32 v160, -v160, v164, v163
	v_fma_f32 v130, -v128, v129, 1.0
	v_div_fmas_f32 v160, v160, v161, v164
	v_fmac_f32_e32 v129, v130, v129
	v_div_fixup_f32 v158, v160, v158, 1.0
	v_div_scale_f32 v131, vcc, 1.0, v159, 1.0
	v_mul_f32_e32 v165, v131, v129
	v_fma_f32 v130, -v128, v165, v131
	v_fmac_f32_e32 v165, v130, v129
	v_fma_f32 v128, -v128, v165, v131
	v_div_fmas_f32 v128, v128, v129, v165
	v_div_fixup_f32 v159, v128, v159, 1.0
	v_pk_mul_f32 v[152:153], v[84:85], v[152:153]
	v_pk_mul_f32 v[154:155], v[86:87], v[154:155]
	v_pk_mul_f32 v[156:157], v[80:81], v[156:157]
	v_pk_mul_f32 v[158:159], v[82:83], v[158:159]
	v_cvt_pk_bf16_f32 v168, v152, v153
	v_cvt_pk_bf16_f32 v169, v154, v155
	v_cvt_pk_bf16_f32 v170, v156, v157
	v_cvt_pk_bf16_f32 v171, v158, v159
	global_store_dwordx4 v186, v[168:171], s[68:69] offset:256
	global_load_dwordx4 v[84:87], v180, s[64:65] offset:256
	s_waitcnt vmcnt(6)
; __device__ __forceinline__ float sigmoidf_(float x) { return 1.f / (1.f + __expf(-x)); }
	v_lshlrev_b32_e32 v152, 16, v108
	v_and_b32_e32 v153, 0xffff0000, v108
	v_lshlrev_b32_e32 v154, 16, v109
	v_and_b32_e32 v155, 0xffff0000, v109
	v_lshlrev_b32_e32 v156, 16, v110
	v_and_b32_e32 v157, 0xffff0000, v110
	v_lshlrev_b32_e32 v158, 16, v111
	v_and_b32_e32 v159, 0xffff0000, v111
	v_mul_f32_e32 v152, 0xbfb8aa3b, v152
	v_mul_f32_e32 v153, 0xbfb8aa3b, v153
	v_mul_f32_e32 v154, 0xbfb8aa3b, v154
	v_mul_f32_e32 v155, 0xbfb8aa3b, v155
	v_mul_f32_e32 v156, 0xbfb8aa3b, v156
	v_mul_f32_e32 v157, 0xbfb8aa3b, v157
	v_mul_f32_e32 v158, 0xbfb8aa3b, v158
	v_mul_f32_e32 v159, 0xbfb8aa3b, v159
	v_exp_f32_e32 v152, v152
	v_exp_f32_e32 v153, v153
	v_exp_f32_e32 v154, v154
	v_exp_f32_e32 v155, v155
	v_exp_f32_e32 v156, v156
	v_exp_f32_e32 v157, v157
	v_exp_f32_e32 v158, v158
	v_exp_f32_e32 v159, v159
	v_pk_add_f32 v[152:153], v[152:153], 1.0 op_sel_hi:[1,0]
	v_pk_add_f32 v[154:155], v[154:155], 1.0 op_sel_hi:[1,0]
	v_pk_add_f32 v[156:157], v[156:157], 1.0 op_sel_hi:[1,0]
	v_pk_add_f32 v[158:159], v[158:159], 1.0 op_sel_hi:[1,0]
	v_div_scale_f32 v160, s[2:3], v152, v152, 1.0
	v_rcp_f32_e32 v161, v160
	s_nop 0
	v_fma_f32 v162, -v160, v161, 1.0
	v_fmac_f32_e32 v161, v162, v161
	v_div_scale_f32 v163, vcc, 1.0, v152, 1.0
	v_mul_f32_e32 v164, v163, v161
	v_div_scale_f32 v128, s[2:3], v153, v153, 1.0
	v_fma_f32 v162, -v160, v164, v163
	v_rcp_f32_e32 v129, v128
	v_fmac_f32_e32 v164, v162, v161
	s_nop 0
	v_fma_f32 v160, -v160, v164, v163
	v_fma_f32 v130, -v128, v129, 1.0
	v_div_fmas_f32 v160, v160, v161, v164
	v_fmac_f32_e32 v129, v130, v129
	v_div_fixup_f32 v152, v160, v152, 1.0
	v_div_scale_f32 v131, vcc, 1.0, v153, 1.0
	v_mul_f32_e32 v165, v131, v129
	v_div_scale_f32 v160, s[2:3], v154, v154, 1.0
	v_fma_f32 v130, -v128, v165, v131
	v_rcp_f32_e32 v161, v160
	v_fmac_f32_e32 v165, v130, v129
	s_nop 0
	v_fma_f32 v128, -v128, v165, v131
	v_fma_f32 v162, -v160, v161, 1.0
	v_div_fmas_f32 v128, v128, v129, v165
	v_fmac_f32_e32 v161, v162, v161
	v_div_fixup_f32 v153, v128, v153, 1.0
	v_div_scale_f32 v163, vcc, 1.0, v154, 1.0
	v_mul_f32_e32 v164, v163, v161
	v_div_scale_f32 v128, s[2:3], v155, v155, 1.0
	v_fma_f32 v162, -v160, v164, v163
	v_rcp_f32_e32 v129, v128
	v_fmac_f32_e32 v164, v162, v161
	s_nop 0
	v_fma_f32 v160, -v160, v164, v163
	v_fma_f32 v130, -v128, v129, 1.0
	v_div_fmas_f32 v160, v160, v161, v164
	v_fmac_f32_e32 v129, v130, v129
	v_div_fixup_f32 v154, v160, v154, 1.0
	v_div_scale_f32 v131, vcc, 1.0, v155, 1.0
	v_mul_f32_e32 v165, v131, v129
	v_div_scale_f32 v160, s[2:3], v156, v156, 1.0
	v_fma_f32 v130, -v128, v165, v131
	v_rcp_f32_e32 v161, v160
	v_fmac_f32_e32 v165, v130, v129
	s_nop 0
	v_fma_f32 v128, -v128, v165, v131
	v_fma_f32 v162, -v160, v161, 1.0
	v_div_fmas_f32 v128, v128, v129, v165
	v_fmac_f32_e32 v161, v162, v161
	v_div_fixup_f32 v155, v128, v155, 1.0
	v_div_scale_f32 v163, vcc, 1.0, v156, 1.0
	v_mul_f32_e32 v164, v163, v161
	v_div_scale_f32 v128, s[2:3], v157, v157, 1.0
	v_fma_f32 v162, -v160, v164, v163
	v_rcp_f32_e32 v129, v128
	v_fmac_f32_e32 v164, v162, v161
	s_nop 0
	v_fma_f32 v160, -v160, v164, v163
	v_fma_f32 v130, -v128, v129, 1.0
	v_div_fmas_f32 v160, v160, v161, v164
	v_fmac_f32_e32 v129, v130, v129
	v_div_fixup_f32 v156, v160, v156, 1.0
	v_div_scale_f32 v131, vcc, 1.0, v157, 1.0
	v_mul_f32_e32 v165, v131, v129
	v_div_scale_f32 v160, s[2:3], v158, v158, 1.0
	v_fma_f32 v130, -v128, v165, v131
	v_rcp_f32_e32 v161, v160
	v_fmac_f32_e32 v165, v130, v129
	s_nop 0
	v_fma_f32 v128, -v128, v165, v131
	v_fma_f32 v162, -v160, v161, 1.0
	v_div_fmas_f32 v128, v128, v129, v165
	v_fmac_f32_e32 v161, v162, v161
	v_div_fixup_f32 v157, v128, v157, 1.0
	v_div_scale_f32 v163, vcc, 1.0, v158, 1.0
	v_mul_f32_e32 v164, v163, v161
	v_div_scale_f32 v128, s[2:3], v159, v159, 1.0
	v_fma_f32 v162, -v160, v164, v163
	v_rcp_f32_e32 v129, v128
	v_fmac_f32_e32 v164, v162, v161
	s_nop 0
	v_fma_f32 v160, -v160, v164, v163
	v_fma_f32 v130, -v128, v129, 1.0
	v_div_fmas_f32 v160, v160, v161, v164
	v_fmac_f32_e32 v129, v130, v129
	v_div_fixup_f32 v158, v160, v158, 1.0
	v_div_scale_f32 v131, vcc, 1.0, v159, 1.0
	v_mul_f32_e32 v165, v131, v129
	v_fma_f32 v130, -v128, v165, v131
	v_fmac_f32_e32 v165, v130, v129
	v_fma_f32 v128, -v128, v165, v131
	v_div_fmas_f32 v128, v128, v129, v165
	v_div_fixup_f32 v159, v128, v159, 1.0
	v_pk_mul_f32 v[152:153], v[76:77], v[152:153]
	v_pk_mul_f32 v[154:155], v[78:79], v[154:155]
	v_pk_mul_f32 v[156:157], v[72:73], v[156:157]
	v_pk_mul_f32 v[158:159], v[74:75], v[158:159]
	v_cvt_pk_bf16_f32 v168, v152, v153
	v_cvt_pk_bf16_f32 v169, v154, v155
	v_cvt_pk_bf16_f32 v170, v156, v157
	v_cvt_pk_bf16_f32 v171, v158, v159
	global_store_dwordx4 v187, v[168:171], s[68:69]
	global_load_dwordx4 v[76:79], v181, s[64:65]
	s_waitcnt vmcnt(6)
; __device__ __forceinline__ float sigmoidf_(float x) { return 1.f / (1.f + __expf(-x)); }
	v_lshlrev_b32_e32 v152, 16, v100
	v_and_b32_e32 v153, 0xffff0000, v100
	v_lshlrev_b32_e32 v154, 16, v101
	v_and_b32_e32 v155, 0xffff0000, v101
	v_lshlrev_b32_e32 v156, 16, v102
	v_and_b32_e32 v157, 0xffff0000, v102
	v_lshlrev_b32_e32 v158, 16, v103
	v_and_b32_e32 v159, 0xffff0000, v103
	v_mul_f32_e32 v152, 0xbfb8aa3b, v152
	v_mul_f32_e32 v153, 0xbfb8aa3b, v153
	v_mul_f32_e32 v154, 0xbfb8aa3b, v154
	v_mul_f32_e32 v155, 0xbfb8aa3b, v155
	v_mul_f32_e32 v156, 0xbfb8aa3b, v156
	v_mul_f32_e32 v157, 0xbfb8aa3b, v157
	v_mul_f32_e32 v158, 0xbfb8aa3b, v158
	v_mul_f32_e32 v159, 0xbfb8aa3b, v159
	v_exp_f32_e32 v152, v152
	v_exp_f32_e32 v153, v153
	v_exp_f32_e32 v154, v154
	v_exp_f32_e32 v155, v155
	v_exp_f32_e32 v156, v156
	v_exp_f32_e32 v157, v157
	v_exp_f32_e32 v158, v158
	v_exp_f32_e32 v159, v159
	v_pk_add_f32 v[152:153], v[152:153], 1.0 op_sel_hi:[1,0]
	v_pk_add_f32 v[154:155], v[154:155], 1.0 op_sel_hi:[1,0]
	v_pk_add_f32 v[156:157], v[156:157], 1.0 op_sel_hi:[1,0]
	v_pk_add_f32 v[158:159], v[158:159], 1.0 op_sel_hi:[1,0]
	v_div_scale_f32 v160, s[2:3], v152, v152, 1.0
	v_rcp_f32_e32 v161, v160
	s_nop 0
	v_fma_f32 v162, -v160, v161, 1.0
	v_fmac_f32_e32 v161, v162, v161
	v_div_scale_f32 v163, vcc, 1.0, v152, 1.0
	v_mul_f32_e32 v164, v163, v161
	v_div_scale_f32 v128, s[2:3], v153, v153, 1.0
	v_fma_f32 v162, -v160, v164, v163
	v_rcp_f32_e32 v129, v128
	v_fmac_f32_e32 v164, v162, v161
	s_nop 0
	v_fma_f32 v160, -v160, v164, v163
	v_fma_f32 v130, -v128, v129, 1.0
	v_div_fmas_f32 v160, v160, v161, v164
	v_fmac_f32_e32 v129, v130, v129
	v_div_fixup_f32 v152, v160, v152, 1.0
	v_div_scale_f32 v131, vcc, 1.0, v153, 1.0
	v_mul_f32_e32 v165, v131, v129
	v_div_scale_f32 v160, s[2:3], v154, v154, 1.0
	v_fma_f32 v130, -v128, v165, v131
	v_rcp_f32_e32 v161, v160
	v_fmac_f32_e32 v165, v130, v129
	s_nop 0
	v_fma_f32 v128, -v128, v165, v131
	v_fma_f32 v162, -v160, v161, 1.0
	v_div_fmas_f32 v128, v128, v129, v165
	v_fmac_f32_e32 v161, v162, v161
	v_div_fixup_f32 v153, v128, v153, 1.0
	v_div_scale_f32 v163, vcc, 1.0, v154, 1.0
	v_mul_f32_e32 v164, v163, v161
	v_div_scale_f32 v128, s[2:3], v155, v155, 1.0
	v_fma_f32 v162, -v160, v164, v163
	v_rcp_f32_e32 v129, v128
	v_fmac_f32_e32 v164, v162, v161
	s_nop 0
	v_fma_f32 v160, -v160, v164, v163
	v_fma_f32 v130, -v128, v129, 1.0
	v_div_fmas_f32 v160, v160, v161, v164
	v_fmac_f32_e32 v129, v130, v129
	v_div_fixup_f32 v154, v160, v154, 1.0
	v_div_scale_f32 v131, vcc, 1.0, v155, 1.0
	v_mul_f32_e32 v165, v131, v129
	v_div_scale_f32 v160, s[2:3], v156, v156, 1.0
	v_fma_f32 v130, -v128, v165, v131
	v_rcp_f32_e32 v161, v160
	v_fmac_f32_e32 v165, v130, v129
	s_nop 0
	v_fma_f32 v128, -v128, v165, v131
	v_fma_f32 v162, -v160, v161, 1.0
	v_div_fmas_f32 v128, v128, v129, v165
	v_fmac_f32_e32 v161, v162, v161
	v_div_fixup_f32 v155, v128, v155, 1.0
	v_div_scale_f32 v163, vcc, 1.0, v156, 1.0
	v_mul_f32_e32 v164, v163, v161
	v_div_scale_f32 v128, s[2:3], v157, v157, 1.0
	v_fma_f32 v162, -v160, v164, v163
	v_rcp_f32_e32 v129, v128
	v_fmac_f32_e32 v164, v162, v161
	s_nop 0
	v_fma_f32 v160, -v160, v164, v163
	v_fma_f32 v130, -v128, v129, 1.0
	v_div_fmas_f32 v160, v160, v161, v164
	v_fmac_f32_e32 v129, v130, v129
	v_div_fixup_f32 v156, v160, v156, 1.0
	v_div_scale_f32 v131, vcc, 1.0, v157, 1.0
	v_mul_f32_e32 v165, v131, v129
	v_div_scale_f32 v160, s[2:3], v158, v158, 1.0
	v_fma_f32 v130, -v128, v165, v131
	v_rcp_f32_e32 v161, v160
	v_fmac_f32_e32 v165, v130, v129
	s_nop 0
	v_fma_f32 v128, -v128, v165, v131
	v_fma_f32 v162, -v160, v161, 1.0
	v_div_fmas_f32 v128, v128, v129, v165
	v_fmac_f32_e32 v161, v162, v161
	v_div_fixup_f32 v157, v128, v157, 1.0
	v_div_scale_f32 v163, vcc, 1.0, v158, 1.0
	v_mul_f32_e32 v164, v163, v161
	v_div_scale_f32 v128, s[2:3], v159, v159, 1.0
	v_fma_f32 v162, -v160, v164, v163
	v_rcp_f32_e32 v129, v128
	v_fmac_f32_e32 v164, v162, v161
	s_nop 0
	v_fma_f32 v160, -v160, v164, v163
	v_fma_f32 v130, -v128, v129, 1.0
	v_div_fmas_f32 v160, v160, v161, v164
	v_fmac_f32_e32 v129, v130, v129
	v_div_fixup_f32 v158, v160, v158, 1.0
	v_div_scale_f32 v131, vcc, 1.0, v159, 1.0
	v_mul_f32_e32 v165, v131, v129
	v_fma_f32 v130, -v128, v165, v131
	v_fmac_f32_e32 v165, v130, v129
	v_fma_f32 v128, -v128, v165, v131
	v_div_fmas_f32 v128, v128, v129, v165
	v_div_fixup_f32 v159, v128, v159, 1.0
	v_pk_mul_f32 v[152:153], v[68:69], v[152:153]
	v_pk_mul_f32 v[154:155], v[70:71], v[154:155]
	v_pk_mul_f32 v[156:157], v[64:65], v[156:157]
	v_pk_mul_f32 v[158:159], v[66:67], v[158:159]
	v_cvt_pk_bf16_f32 v168, v152, v153
	v_cvt_pk_bf16_f32 v169, v154, v155
	v_cvt_pk_bf16_f32 v170, v156, v157
	v_cvt_pk_bf16_f32 v171, v158, v159
	global_store_dwordx4 v187, v[168:171], s[68:69] offset:256
	global_load_dwordx4 v[68:71], v181, s[64:65] offset:256
	s_waitcnt vmcnt(6)
; __device__ __forceinline__ float sigmoidf_(float x) { return 1.f / (1.f + __expf(-x)); }
	v_lshlrev_b32_e32 v152, 16, v92
	v_and_b32_e32 v153, 0xffff0000, v92
	v_lshlrev_b32_e32 v154, 16, v93
	v_and_b32_e32 v155, 0xffff0000, v93
	v_lshlrev_b32_e32 v156, 16, v94
	v_and_b32_e32 v157, 0xffff0000, v94
	v_lshlrev_b32_e32 v158, 16, v95
	v_and_b32_e32 v159, 0xffff0000, v95
	v_mul_f32_e32 v152, 0xbfb8aa3b, v152
	v_mul_f32_e32 v153, 0xbfb8aa3b, v153
	v_mul_f32_e32 v154, 0xbfb8aa3b, v154
	v_mul_f32_e32 v155, 0xbfb8aa3b, v155
	v_mul_f32_e32 v156, 0xbfb8aa3b, v156
	v_mul_f32_e32 v157, 0xbfb8aa3b, v157
	v_mul_f32_e32 v158, 0xbfb8aa3b, v158
	v_mul_f32_e32 v159, 0xbfb8aa3b, v159
	v_exp_f32_e32 v152, v152
	v_exp_f32_e32 v153, v153
	v_exp_f32_e32 v154, v154
	v_exp_f32_e32 v155, v155
	v_exp_f32_e32 v156, v156
	v_exp_f32_e32 v157, v157
	v_exp_f32_e32 v158, v158
	v_exp_f32_e32 v159, v159
	v_pk_add_f32 v[152:153], v[152:153], 1.0 op_sel_hi:[1,0]
	v_pk_add_f32 v[154:155], v[154:155], 1.0 op_sel_hi:[1,0]
	v_pk_add_f32 v[156:157], v[156:157], 1.0 op_sel_hi:[1,0]
	v_pk_add_f32 v[158:159], v[158:159], 1.0 op_sel_hi:[1,0]
	v_div_scale_f32 v160, s[2:3], v152, v152, 1.0
	v_rcp_f32_e32 v161, v160
	s_nop 0
	v_fma_f32 v162, -v160, v161, 1.0
	v_fmac_f32_e32 v161, v162, v161
	v_div_scale_f32 v163, vcc, 1.0, v152, 1.0
	v_mul_f32_e32 v164, v163, v161
	v_div_scale_f32 v128, s[2:3], v153, v153, 1.0
	v_fma_f32 v162, -v160, v164, v163
	v_rcp_f32_e32 v129, v128
	v_fmac_f32_e32 v164, v162, v161
	s_nop 0
	v_fma_f32 v160, -v160, v164, v163
	v_fma_f32 v130, -v128, v129, 1.0
	v_div_fmas_f32 v160, v160, v161, v164
	v_fmac_f32_e32 v129, v130, v129
	v_div_fixup_f32 v152, v160, v152, 1.0
	v_div_scale_f32 v131, vcc, 1.0, v153, 1.0
	v_mul_f32_e32 v165, v131, v129
	v_div_scale_f32 v160, s[2:3], v154, v154, 1.0
	v_fma_f32 v130, -v128, v165, v131
	v_rcp_f32_e32 v161, v160
	v_fmac_f32_e32 v165, v130, v129
	s_nop 0
	v_fma_f32 v128, -v128, v165, v131
	v_fma_f32 v162, -v160, v161, 1.0
	v_div_fmas_f32 v128, v128, v129, v165
	v_fmac_f32_e32 v161, v162, v161
	v_div_fixup_f32 v153, v128, v153, 1.0
	v_div_scale_f32 v163, vcc, 1.0, v154, 1.0
	v_mul_f32_e32 v164, v163, v161
	v_div_scale_f32 v128, s[2:3], v155, v155, 1.0
	v_fma_f32 v162, -v160, v164, v163
	v_rcp_f32_e32 v129, v128
	v_fmac_f32_e32 v164, v162, v161
	s_nop 0
	v_fma_f32 v160, -v160, v164, v163
	v_fma_f32 v130, -v128, v129, 1.0
	v_div_fmas_f32 v160, v160, v161, v164
	v_fmac_f32_e32 v129, v130, v129
	v_div_fixup_f32 v154, v160, v154, 1.0
	v_div_scale_f32 v131, vcc, 1.0, v155, 1.0
	v_mul_f32_e32 v165, v131, v129
	v_div_scale_f32 v160, s[2:3], v156, v156, 1.0
	v_fma_f32 v130, -v128, v165, v131
	v_rcp_f32_e32 v161, v160
	v_fmac_f32_e32 v165, v130, v129
	s_nop 0
	v_fma_f32 v128, -v128, v165, v131
	v_fma_f32 v162, -v160, v161, 1.0
	v_div_fmas_f32 v128, v128, v129, v165
	v_fmac_f32_e32 v161, v162, v161
	v_div_fixup_f32 v155, v128, v155, 1.0
	v_div_scale_f32 v163, vcc, 1.0, v156, 1.0
	v_mul_f32_e32 v164, v163, v161
	v_div_scale_f32 v128, s[2:3], v157, v157, 1.0
	v_fma_f32 v162, -v160, v164, v163
	v_rcp_f32_e32 v129, v128
	v_fmac_f32_e32 v164, v162, v161
	s_nop 0
	v_fma_f32 v160, -v160, v164, v163
	v_fma_f32 v130, -v128, v129, 1.0
	v_div_fmas_f32 v160, v160, v161, v164
	v_fmac_f32_e32 v129, v130, v129
	v_div_fixup_f32 v156, v160, v156, 1.0
	v_div_scale_f32 v131, vcc, 1.0, v157, 1.0
	v_mul_f32_e32 v165, v131, v129
	v_div_scale_f32 v160, s[2:3], v158, v158, 1.0
	v_fma_f32 v130, -v128, v165, v131
	v_rcp_f32_e32 v161, v160
	v_fmac_f32_e32 v165, v130, v129
	s_nop 0
	v_fma_f32 v128, -v128, v165, v131
	v_fma_f32 v162, -v160, v161, 1.0
	v_div_fmas_f32 v128, v128, v129, v165
	v_fmac_f32_e32 v161, v162, v161
	v_div_fixup_f32 v157, v128, v157, 1.0
	v_div_scale_f32 v163, vcc, 1.0, v158, 1.0
	v_mul_f32_e32 v164, v163, v161
	v_div_scale_f32 v128, s[2:3], v159, v159, 1.0
	v_fma_f32 v162, -v160, v164, v163
	v_rcp_f32_e32 v129, v128
	v_fmac_f32_e32 v164, v162, v161
	s_nop 0
	v_fma_f32 v160, -v160, v164, v163
	v_fma_f32 v130, -v128, v129, 1.0
	v_div_fmas_f32 v160, v160, v161, v164
	v_fmac_f32_e32 v129, v130, v129
	v_div_fixup_f32 v158, v160, v158, 1.0
	v_div_scale_f32 v131, vcc, 1.0, v159, 1.0
	v_mul_f32_e32 v165, v131, v129
	v_fma_f32 v130, -v128, v165, v131
	v_fmac_f32_e32 v165, v130, v129
	v_fma_f32 v128, -v128, v165, v131
	v_div_fmas_f32 v128, v128, v129, v165
	v_div_fixup_f32 v159, v128, v159, 1.0
	v_pk_mul_f32 v[152:153], v[60:61], v[152:153]
	v_pk_mul_f32 v[154:155], v[62:63], v[154:155]
	v_pk_mul_f32 v[156:157], v[56:57], v[156:157]
	v_pk_mul_f32 v[158:159], v[58:59], v[158:159]
	v_cvt_pk_bf16_f32 v168, v152, v153
	v_cvt_pk_bf16_f32 v169, v154, v155
	v_cvt_pk_bf16_f32 v170, v156, v157
	v_cvt_pk_bf16_f32 v171, v158, v159
	global_store_dwordx4 v188, v[168:171], s[68:69]
	global_load_dwordx4 v[60:63], v182, s[64:65]
	s_waitcnt vmcnt(6)
; __device__ __forceinline__ float sigmoidf_(float x) { return 1.f / (1.f + __expf(-x)); }
	v_lshlrev_b32_e32 v152, 16, v84
	v_and_b32_e32 v153, 0xffff0000, v84
	v_lshlrev_b32_e32 v154, 16, v85
	v_and_b32_e32 v155, 0xffff0000, v85
	v_lshlrev_b32_e32 v156, 16, v86
	v_and_b32_e32 v157, 0xffff0000, v86
	v_lshlrev_b32_e32 v158, 16, v87
	v_and_b32_e32 v159, 0xffff0000, v87
	v_mul_f32_e32 v152, 0xbfb8aa3b, v152
	v_mul_f32_e32 v153, 0xbfb8aa3b, v153
	v_mul_f32_e32 v154, 0xbfb8aa3b, v154
	v_mul_f32_e32 v155, 0xbfb8aa3b, v155
	v_mul_f32_e32 v156, 0xbfb8aa3b, v156
	v_mul_f32_e32 v157, 0xbfb8aa3b, v157
	v_mul_f32_e32 v158, 0xbfb8aa3b, v158
	v_mul_f32_e32 v159, 0xbfb8aa3b, v159
	v_exp_f32_e32 v152, v152
	v_exp_f32_e32 v153, v153
	v_exp_f32_e32 v154, v154
	v_exp_f32_e32 v155, v155
	v_exp_f32_e32 v156, v156
	v_exp_f32_e32 v157, v157
	v_exp_f32_e32 v158, v158
	v_exp_f32_e32 v159, v159
	v_pk_add_f32 v[152:153], v[152:153], 1.0 op_sel_hi:[1,0]
	v_pk_add_f32 v[154:155], v[154:155], 1.0 op_sel_hi:[1,0]
	v_pk_add_f32 v[156:157], v[156:157], 1.0 op_sel_hi:[1,0]
	v_pk_add_f32 v[158:159], v[158:159], 1.0 op_sel_hi:[1,0]
	v_div_scale_f32 v160, s[2:3], v152, v152, 1.0
	v_rcp_f32_e32 v161, v160
	s_nop 0
	v_fma_f32 v162, -v160, v161, 1.0
	v_fmac_f32_e32 v161, v162, v161
	v_div_scale_f32 v163, vcc, 1.0, v152, 1.0
	v_mul_f32_e32 v164, v163, v161
	v_div_scale_f32 v128, s[2:3], v153, v153, 1.0
	v_fma_f32 v162, -v160, v164, v163
	v_rcp_f32_e32 v129, v128
	v_fmac_f32_e32 v164, v162, v161
	s_nop 0
	v_fma_f32 v160, -v160, v164, v163
	v_fma_f32 v130, -v128, v129, 1.0
	v_div_fmas_f32 v160, v160, v161, v164
	v_fmac_f32_e32 v129, v130, v129
	v_div_fixup_f32 v152, v160, v152, 1.0
	v_div_scale_f32 v131, vcc, 1.0, v153, 1.0
	v_mul_f32_e32 v165, v131, v129
	v_div_scale_f32 v160, s[2:3], v154, v154, 1.0
	v_fma_f32 v130, -v128, v165, v131
	v_rcp_f32_e32 v161, v160
	v_fmac_f32_e32 v165, v130, v129
	s_nop 0
	v_fma_f32 v128, -v128, v165, v131
	v_fma_f32 v162, -v160, v161, 1.0
	v_div_fmas_f32 v128, v128, v129, v165
	v_fmac_f32_e32 v161, v162, v161
	v_div_fixup_f32 v153, v128, v153, 1.0
	v_div_scale_f32 v163, vcc, 1.0, v154, 1.0
	v_mul_f32_e32 v164, v163, v161
	v_div_scale_f32 v128, s[2:3], v155, v155, 1.0
	v_fma_f32 v162, -v160, v164, v163
	v_rcp_f32_e32 v129, v128
	v_fmac_f32_e32 v164, v162, v161
	s_nop 0
	v_fma_f32 v160, -v160, v164, v163
	v_fma_f32 v130, -v128, v129, 1.0
	v_div_fmas_f32 v160, v160, v161, v164
	v_fmac_f32_e32 v129, v130, v129
	v_div_fixup_f32 v154, v160, v154, 1.0
	v_div_scale_f32 v131, vcc, 1.0, v155, 1.0
	v_mul_f32_e32 v165, v131, v129
	v_div_scale_f32 v160, s[2:3], v156, v156, 1.0
	v_fma_f32 v130, -v128, v165, v131
	v_rcp_f32_e32 v161, v160
	v_fmac_f32_e32 v165, v130, v129
	s_nop 0
	v_fma_f32 v128, -v128, v165, v131
	v_fma_f32 v162, -v160, v161, 1.0
	v_div_fmas_f32 v128, v128, v129, v165
	v_fmac_f32_e32 v161, v162, v161
	v_div_fixup_f32 v155, v128, v155, 1.0
	v_div_scale_f32 v163, vcc, 1.0, v156, 1.0
	v_mul_f32_e32 v164, v163, v161
	v_div_scale_f32 v128, s[2:3], v157, v157, 1.0
	v_fma_f32 v162, -v160, v164, v163
	v_rcp_f32_e32 v129, v128
	v_fmac_f32_e32 v164, v162, v161
	s_nop 0
	v_fma_f32 v160, -v160, v164, v163
	v_fma_f32 v130, -v128, v129, 1.0
	v_div_fmas_f32 v160, v160, v161, v164
	v_fmac_f32_e32 v129, v130, v129
	v_div_fixup_f32 v156, v160, v156, 1.0
	v_div_scale_f32 v131, vcc, 1.0, v157, 1.0
	v_mul_f32_e32 v165, v131, v129
	v_div_scale_f32 v160, s[2:3], v158, v158, 1.0
	v_fma_f32 v130, -v128, v165, v131
	v_rcp_f32_e32 v161, v160
	v_fmac_f32_e32 v165, v130, v129
	s_nop 0
	v_fma_f32 v128, -v128, v165, v131
	v_fma_f32 v162, -v160, v161, 1.0
	v_div_fmas_f32 v128, v128, v129, v165
	v_fmac_f32_e32 v161, v162, v161
	v_div_fixup_f32 v157, v128, v157, 1.0
	v_div_scale_f32 v163, vcc, 1.0, v158, 1.0
	v_mul_f32_e32 v164, v163, v161
	v_div_scale_f32 v128, s[2:3], v159, v159, 1.0
	v_fma_f32 v162, -v160, v164, v163
	v_rcp_f32_e32 v129, v128
	v_fmac_f32_e32 v164, v162, v161
	s_nop 0
	v_fma_f32 v160, -v160, v164, v163
	v_fma_f32 v130, -v128, v129, 1.0
	v_div_fmas_f32 v160, v160, v161, v164
	v_fmac_f32_e32 v129, v130, v129
	v_div_fixup_f32 v158, v160, v158, 1.0
	v_div_scale_f32 v131, vcc, 1.0, v159, 1.0
	v_mul_f32_e32 v165, v131, v129
	v_fma_f32 v130, -v128, v165, v131
	v_fmac_f32_e32 v165, v130, v129
	v_fma_f32 v128, -v128, v165, v131
	v_div_fmas_f32 v128, v128, v129, v165
	v_div_fixup_f32 v159, v128, v159, 1.0
	v_pk_mul_f32 v[152:153], v[52:53], v[152:153]
	v_pk_mul_f32 v[154:155], v[54:55], v[154:155]
	v_pk_mul_f32 v[156:157], v[48:49], v[156:157]
	v_pk_mul_f32 v[158:159], v[50:51], v[158:159]
	v_cvt_pk_bf16_f32 v168, v152, v153
	v_cvt_pk_bf16_f32 v169, v154, v155
	v_cvt_pk_bf16_f32 v170, v156, v157
	v_cvt_pk_bf16_f32 v171, v158, v159
	global_store_dwordx4 v188, v[168:171], s[68:69] offset:256
	global_load_dwordx4 v[52:55], v182, s[64:65] offset:256
	s_waitcnt vmcnt(6)
; __device__ __forceinline__ float sigmoidf_(float x) { return 1.f / (1.f + __expf(-x)); }
	v_lshlrev_b32_e32 v152, 16, v76
	v_and_b32_e32 v153, 0xffff0000, v76
	v_lshlrev_b32_e32 v154, 16, v77
	v_and_b32_e32 v155, 0xffff0000, v77
	v_lshlrev_b32_e32 v156, 16, v78
	v_and_b32_e32 v157, 0xffff0000, v78
	v_lshlrev_b32_e32 v158, 16, v79
	v_and_b32_e32 v159, 0xffff0000, v79
	v_mul_f32_e32 v152, 0xbfb8aa3b, v152
	v_mul_f32_e32 v153, 0xbfb8aa3b, v153
	v_mul_f32_e32 v154, 0xbfb8aa3b, v154
	v_mul_f32_e32 v155, 0xbfb8aa3b, v155
	v_mul_f32_e32 v156, 0xbfb8aa3b, v156
	v_mul_f32_e32 v157, 0xbfb8aa3b, v157
	v_mul_f32_e32 v158, 0xbfb8aa3b, v158
	v_mul_f32_e32 v159, 0xbfb8aa3b, v159
	v_exp_f32_e32 v152, v152
	v_exp_f32_e32 v153, v153
	v_exp_f32_e32 v154, v154
	v_exp_f32_e32 v155, v155
	v_exp_f32_e32 v156, v156
	v_exp_f32_e32 v157, v157
	v_exp_f32_e32 v158, v158
	v_exp_f32_e32 v159, v159
	v_pk_add_f32 v[152:153], v[152:153], 1.0 op_sel_hi:[1,0]
	v_pk_add_f32 v[154:155], v[154:155], 1.0 op_sel_hi:[1,0]
	v_pk_add_f32 v[156:157], v[156:157], 1.0 op_sel_hi:[1,0]
	v_pk_add_f32 v[158:159], v[158:159], 1.0 op_sel_hi:[1,0]
	v_div_scale_f32 v160, s[2:3], v152, v152, 1.0
	v_rcp_f32_e32 v161, v160
	s_nop 0
	v_fma_f32 v162, -v160, v161, 1.0
	v_fmac_f32_e32 v161, v162, v161
	v_div_scale_f32 v163, vcc, 1.0, v152, 1.0
	v_mul_f32_e32 v164, v163, v161
	v_div_scale_f32 v128, s[2:3], v153, v153, 1.0
	v_fma_f32 v162, -v160, v164, v163
	v_rcp_f32_e32 v129, v128
	v_fmac_f32_e32 v164, v162, v161
	s_nop 0
	v_fma_f32 v160, -v160, v164, v163
	v_fma_f32 v130, -v128, v129, 1.0
	v_div_fmas_f32 v160, v160, v161, v164
	v_fmac_f32_e32 v129, v130, v129
	v_div_fixup_f32 v152, v160, v152, 1.0
	v_div_scale_f32 v131, vcc, 1.0, v153, 1.0
	v_mul_f32_e32 v165, v131, v129
	v_div_scale_f32 v160, s[2:3], v154, v154, 1.0
	v_fma_f32 v130, -v128, v165, v131
	v_rcp_f32_e32 v161, v160
	v_fmac_f32_e32 v165, v130, v129
	s_nop 0
	v_fma_f32 v128, -v128, v165, v131
	v_fma_f32 v162, -v160, v161, 1.0
	v_div_fmas_f32 v128, v128, v129, v165
	v_fmac_f32_e32 v161, v162, v161
	v_div_fixup_f32 v153, v128, v153, 1.0
	v_div_scale_f32 v163, vcc, 1.0, v154, 1.0
	v_mul_f32_e32 v164, v163, v161
	v_div_scale_f32 v128, s[2:3], v155, v155, 1.0
	v_fma_f32 v162, -v160, v164, v163
	v_rcp_f32_e32 v129, v128
	v_fmac_f32_e32 v164, v162, v161
	s_nop 0
	v_fma_f32 v160, -v160, v164, v163
	v_fma_f32 v130, -v128, v129, 1.0
	v_div_fmas_f32 v160, v160, v161, v164
	v_fmac_f32_e32 v129, v130, v129
	v_div_fixup_f32 v154, v160, v154, 1.0
	v_div_scale_f32 v131, vcc, 1.0, v155, 1.0
	v_mul_f32_e32 v165, v131, v129
	v_div_scale_f32 v160, s[2:3], v156, v156, 1.0
	v_fma_f32 v130, -v128, v165, v131
	v_rcp_f32_e32 v161, v160
	v_fmac_f32_e32 v165, v130, v129
	s_nop 0
	v_fma_f32 v128, -v128, v165, v131
	v_fma_f32 v162, -v160, v161, 1.0
	v_div_fmas_f32 v128, v128, v129, v165
	v_fmac_f32_e32 v161, v162, v161
	v_div_fixup_f32 v155, v128, v155, 1.0
	v_div_scale_f32 v163, vcc, 1.0, v156, 1.0
	v_mul_f32_e32 v164, v163, v161
	v_div_scale_f32 v128, s[2:3], v157, v157, 1.0
	v_fma_f32 v162, -v160, v164, v163
	v_rcp_f32_e32 v129, v128
	v_fmac_f32_e32 v164, v162, v161
	s_nop 0
	v_fma_f32 v160, -v160, v164, v163
	v_fma_f32 v130, -v128, v129, 1.0
	v_div_fmas_f32 v160, v160, v161, v164
	v_fmac_f32_e32 v129, v130, v129
	v_div_fixup_f32 v156, v160, v156, 1.0
	v_div_scale_f32 v131, vcc, 1.0, v157, 1.0
	v_mul_f32_e32 v165, v131, v129
	v_div_scale_f32 v160, s[2:3], v158, v158, 1.0
	v_fma_f32 v130, -v128, v165, v131
	v_rcp_f32_e32 v161, v160
	v_fmac_f32_e32 v165, v130, v129
	s_nop 0
	v_fma_f32 v128, -v128, v165, v131
	v_fma_f32 v162, -v160, v161, 1.0
	v_div_fmas_f32 v128, v128, v129, v165
	v_fmac_f32_e32 v161, v162, v161
	v_div_fixup_f32 v157, v128, v157, 1.0
	v_div_scale_f32 v163, vcc, 1.0, v158, 1.0
	v_mul_f32_e32 v164, v163, v161
	v_div_scale_f32 v128, s[2:3], v159, v159, 1.0
	v_fma_f32 v162, -v160, v164, v163
	v_rcp_f32_e32 v129, v128
	v_fmac_f32_e32 v164, v162, v161
	s_nop 0
	v_fma_f32 v160, -v160, v164, v163
	v_fma_f32 v130, -v128, v129, 1.0
	v_div_fmas_f32 v160, v160, v161, v164
	v_fmac_f32_e32 v129, v130, v129
	v_div_fixup_f32 v158, v160, v158, 1.0
	v_div_scale_f32 v131, vcc, 1.0, v159, 1.0
	v_mul_f32_e32 v165, v131, v129
	v_fma_f32 v130, -v128, v165, v131
	v_fmac_f32_e32 v165, v130, v129
	v_fma_f32 v128, -v128, v165, v131
	v_div_fmas_f32 v128, v128, v129, v165
	v_div_fixup_f32 v159, v128, v159, 1.0
	v_pk_mul_f32 v[152:153], v[44:45], v[152:153]
	v_pk_mul_f32 v[154:155], v[46:47], v[154:155]
	v_pk_mul_f32 v[156:157], v[40:41], v[156:157]
	v_pk_mul_f32 v[158:159], v[42:43], v[158:159]
	v_cvt_pk_bf16_f32 v168, v152, v153
	v_cvt_pk_bf16_f32 v169, v154, v155
	v_cvt_pk_bf16_f32 v170, v156, v157
	v_cvt_pk_bf16_f32 v171, v158, v159
	global_store_dwordx4 v189, v[168:171], s[68:69]
	global_load_dwordx4 v[44:47], v183, s[64:65]
	s_waitcnt vmcnt(6)
; __device__ __forceinline__ float sigmoidf_(float x) { return 1.f / (1.f + __expf(-x)); }
	v_lshlrev_b32_e32 v152, 16, v68
	v_and_b32_e32 v153, 0xffff0000, v68
	v_lshlrev_b32_e32 v154, 16, v69
	v_and_b32_e32 v155, 0xffff0000, v69
	v_lshlrev_b32_e32 v156, 16, v70
	v_and_b32_e32 v157, 0xffff0000, v70
	v_lshlrev_b32_e32 v158, 16, v71
	v_and_b32_e32 v159, 0xffff0000, v71
	v_mul_f32_e32 v152, 0xbfb8aa3b, v152
	v_mul_f32_e32 v153, 0xbfb8aa3b, v153
	v_mul_f32_e32 v154, 0xbfb8aa3b, v154
	v_mul_f32_e32 v155, 0xbfb8aa3b, v155
	v_mul_f32_e32 v156, 0xbfb8aa3b, v156
	v_mul_f32_e32 v157, 0xbfb8aa3b, v157
	v_mul_f32_e32 v158, 0xbfb8aa3b, v158
	v_mul_f32_e32 v159, 0xbfb8aa3b, v159
	v_exp_f32_e32 v152, v152
	v_exp_f32_e32 v153, v153
	v_exp_f32_e32 v154, v154
	v_exp_f32_e32 v155, v155
	v_exp_f32_e32 v156, v156
	v_exp_f32_e32 v157, v157
	v_exp_f32_e32 v158, v158
	v_exp_f32_e32 v159, v159
	v_pk_add_f32 v[152:153], v[152:153], 1.0 op_sel_hi:[1,0]
	v_pk_add_f32 v[154:155], v[154:155], 1.0 op_sel_hi:[1,0]
	v_pk_add_f32 v[156:157], v[156:157], 1.0 op_sel_hi:[1,0]
	v_pk_add_f32 v[158:159], v[158:159], 1.0 op_sel_hi:[1,0]
	v_div_scale_f32 v160, s[2:3], v152, v152, 1.0
	v_rcp_f32_e32 v161, v160
	s_nop 0
	v_fma_f32 v162, -v160, v161, 1.0
	v_fmac_f32_e32 v161, v162, v161
	v_div_scale_f32 v163, vcc, 1.0, v152, 1.0
	v_mul_f32_e32 v164, v163, v161
	v_div_scale_f32 v128, s[2:3], v153, v153, 1.0
	v_fma_f32 v162, -v160, v164, v163
	v_rcp_f32_e32 v129, v128
	v_fmac_f32_e32 v164, v162, v161
	s_nop 0
	v_fma_f32 v160, -v160, v164, v163
	v_fma_f32 v130, -v128, v129, 1.0
	v_div_fmas_f32 v160, v160, v161, v164
	v_fmac_f32_e32 v129, v130, v129
	v_div_fixup_f32 v152, v160, v152, 1.0
	v_div_scale_f32 v131, vcc, 1.0, v153, 1.0
	v_mul_f32_e32 v165, v131, v129
	v_div_scale_f32 v160, s[2:3], v154, v154, 1.0
	v_fma_f32 v130, -v128, v165, v131
	v_rcp_f32_e32 v161, v160
	v_fmac_f32_e32 v165, v130, v129
	s_nop 0
	v_fma_f32 v128, -v128, v165, v131
	v_fma_f32 v162, -v160, v161, 1.0
	v_div_fmas_f32 v128, v128, v129, v165
	v_fmac_f32_e32 v161, v162, v161
	v_div_fixup_f32 v153, v128, v153, 1.0
	v_div_scale_f32 v163, vcc, 1.0, v154, 1.0
	v_mul_f32_e32 v164, v163, v161
	v_div_scale_f32 v128, s[2:3], v155, v155, 1.0
	v_fma_f32 v162, -v160, v164, v163
	v_rcp_f32_e32 v129, v128
	v_fmac_f32_e32 v164, v162, v161
	s_nop 0
	v_fma_f32 v160, -v160, v164, v163
	v_fma_f32 v130, -v128, v129, 1.0
	v_div_fmas_f32 v160, v160, v161, v164
	v_fmac_f32_e32 v129, v130, v129
	v_div_fixup_f32 v154, v160, v154, 1.0
	v_div_scale_f32 v131, vcc, 1.0, v155, 1.0
	v_mul_f32_e32 v165, v131, v129
	v_div_scale_f32 v160, s[2:3], v156, v156, 1.0
	v_fma_f32 v130, -v128, v165, v131
	v_rcp_f32_e32 v161, v160
	v_fmac_f32_e32 v165, v130, v129
	s_nop 0
	v_fma_f32 v128, -v128, v165, v131
	v_fma_f32 v162, -v160, v161, 1.0
	v_div_fmas_f32 v128, v128, v129, v165
	v_fmac_f32_e32 v161, v162, v161
	v_div_fixup_f32 v155, v128, v155, 1.0
	v_div_scale_f32 v163, vcc, 1.0, v156, 1.0
	v_mul_f32_e32 v164, v163, v161
	v_div_scale_f32 v128, s[2:3], v157, v157, 1.0
	v_fma_f32 v162, -v160, v164, v163
	v_rcp_f32_e32 v129, v128
	v_fmac_f32_e32 v164, v162, v161
	s_nop 0
	v_fma_f32 v160, -v160, v164, v163
	v_fma_f32 v130, -v128, v129, 1.0
	v_div_fmas_f32 v160, v160, v161, v164
	v_fmac_f32_e32 v129, v130, v129
	v_div_fixup_f32 v156, v160, v156, 1.0
	v_div_scale_f32 v131, vcc, 1.0, v157, 1.0
	v_mul_f32_e32 v165, v131, v129
	v_div_scale_f32 v160, s[2:3], v158, v158, 1.0
	v_fma_f32 v130, -v128, v165, v131
	v_rcp_f32_e32 v161, v160
	v_fmac_f32_e32 v165, v130, v129
	s_nop 0
	v_fma_f32 v128, -v128, v165, v131
	v_fma_f32 v162, -v160, v161, 1.0
	v_div_fmas_f32 v128, v128, v129, v165
	v_fmac_f32_e32 v161, v162, v161
	v_div_fixup_f32 v157, v128, v157, 1.0
	v_div_scale_f32 v163, vcc, 1.0, v158, 1.0
	v_mul_f32_e32 v164, v163, v161
	v_div_scale_f32 v128, s[2:3], v159, v159, 1.0
	v_fma_f32 v162, -v160, v164, v163
	v_rcp_f32_e32 v129, v128
	v_fmac_f32_e32 v164, v162, v161
	s_nop 0
	v_fma_f32 v160, -v160, v164, v163
	v_fma_f32 v130, -v128, v129, 1.0
	v_div_fmas_f32 v160, v160, v161, v164
	v_fmac_f32_e32 v129, v130, v129
	v_div_fixup_f32 v158, v160, v158, 1.0
	v_div_scale_f32 v131, vcc, 1.0, v159, 1.0
	v_mul_f32_e32 v165, v131, v129
	v_fma_f32 v130, -v128, v165, v131
	v_fmac_f32_e32 v165, v130, v129
	v_fma_f32 v128, -v128, v165, v131
	v_div_fmas_f32 v128, v128, v129, v165
	v_div_fixup_f32 v159, v128, v159, 1.0
	v_pk_mul_f32 v[152:153], v[36:37], v[152:153]
	v_pk_mul_f32 v[154:155], v[38:39], v[154:155]
	v_pk_mul_f32 v[156:157], v[32:33], v[156:157]
	v_pk_mul_f32 v[158:159], v[34:35], v[158:159]
	v_cvt_pk_bf16_f32 v168, v152, v153
	v_cvt_pk_bf16_f32 v169, v154, v155
	v_cvt_pk_bf16_f32 v170, v156, v157
	v_cvt_pk_bf16_f32 v171, v158, v159
	global_store_dwordx4 v189, v[168:171], s[68:69] offset:256
	global_load_dwordx4 v[36:39], v183, s[64:65] offset:256
	s_waitcnt vmcnt(6)
; __device__ __forceinline__ float sigmoidf_(float x) { return 1.f / (1.f + __expf(-x)); }
	v_lshlrev_b32_e32 v152, 16, v60
	v_and_b32_e32 v153, 0xffff0000, v60
	v_lshlrev_b32_e32 v154, 16, v61
	v_and_b32_e32 v155, 0xffff0000, v61
	v_lshlrev_b32_e32 v156, 16, v62
	v_and_b32_e32 v157, 0xffff0000, v62
	v_lshlrev_b32_e32 v158, 16, v63
	v_and_b32_e32 v159, 0xffff0000, v63
	v_mul_f32_e32 v152, 0xbfb8aa3b, v152
	v_mul_f32_e32 v153, 0xbfb8aa3b, v153
	v_mul_f32_e32 v154, 0xbfb8aa3b, v154
	v_mul_f32_e32 v155, 0xbfb8aa3b, v155
	v_mul_f32_e32 v156, 0xbfb8aa3b, v156
	v_mul_f32_e32 v157, 0xbfb8aa3b, v157
	v_mul_f32_e32 v158, 0xbfb8aa3b, v158
	v_mul_f32_e32 v159, 0xbfb8aa3b, v159
	v_exp_f32_e32 v152, v152
	v_exp_f32_e32 v153, v153
	v_exp_f32_e32 v154, v154
	v_exp_f32_e32 v155, v155
	v_exp_f32_e32 v156, v156
	v_exp_f32_e32 v157, v157
	v_exp_f32_e32 v158, v158
	v_exp_f32_e32 v159, v159
	v_pk_add_f32 v[152:153], v[152:153], 1.0 op_sel_hi:[1,0]
	v_pk_add_f32 v[154:155], v[154:155], 1.0 op_sel_hi:[1,0]
	v_pk_add_f32 v[156:157], v[156:157], 1.0 op_sel_hi:[1,0]
	v_pk_add_f32 v[158:159], v[158:159], 1.0 op_sel_hi:[1,0]
	v_div_scale_f32 v160, s[2:3], v152, v152, 1.0
	v_rcp_f32_e32 v161, v160
	s_nop 0
	v_fma_f32 v162, -v160, v161, 1.0
	v_fmac_f32_e32 v161, v162, v161
	v_div_scale_f32 v163, vcc, 1.0, v152, 1.0
	v_mul_f32_e32 v164, v163, v161
	v_div_scale_f32 v128, s[2:3], v153, v153, 1.0
	v_fma_f32 v162, -v160, v164, v163
	v_rcp_f32_e32 v129, v128
	v_fmac_f32_e32 v164, v162, v161
	s_nop 0
	v_fma_f32 v160, -v160, v164, v163
	v_fma_f32 v130, -v128, v129, 1.0
	v_div_fmas_f32 v160, v160, v161, v164
	v_fmac_f32_e32 v129, v130, v129
	v_div_fixup_f32 v152, v160, v152, 1.0
	v_div_scale_f32 v131, vcc, 1.0, v153, 1.0
	v_mul_f32_e32 v165, v131, v129
	v_div_scale_f32 v160, s[2:3], v154, v154, 1.0
	v_fma_f32 v130, -v128, v165, v131
	v_rcp_f32_e32 v161, v160
	v_fmac_f32_e32 v165, v130, v129
	s_nop 0
	v_fma_f32 v128, -v128, v165, v131
	v_fma_f32 v162, -v160, v161, 1.0
	v_div_fmas_f32 v128, v128, v129, v165
	v_fmac_f32_e32 v161, v162, v161
	v_div_fixup_f32 v153, v128, v153, 1.0
	v_div_scale_f32 v163, vcc, 1.0, v154, 1.0
	v_mul_f32_e32 v164, v163, v161
	v_div_scale_f32 v128, s[2:3], v155, v155, 1.0
	v_fma_f32 v162, -v160, v164, v163
	v_rcp_f32_e32 v129, v128
	v_fmac_f32_e32 v164, v162, v161
	s_nop 0
	v_fma_f32 v160, -v160, v164, v163
	v_fma_f32 v130, -v128, v129, 1.0
	v_div_fmas_f32 v160, v160, v161, v164
	v_fmac_f32_e32 v129, v130, v129
	v_div_fixup_f32 v154, v160, v154, 1.0
	v_div_scale_f32 v131, vcc, 1.0, v155, 1.0
	v_mul_f32_e32 v165, v131, v129
	v_div_scale_f32 v160, s[2:3], v156, v156, 1.0
	v_fma_f32 v130, -v128, v165, v131
	v_rcp_f32_e32 v161, v160
	v_fmac_f32_e32 v165, v130, v129
	s_nop 0
	v_fma_f32 v128, -v128, v165, v131
	v_fma_f32 v162, -v160, v161, 1.0
	v_div_fmas_f32 v128, v128, v129, v165
	v_fmac_f32_e32 v161, v162, v161
	v_div_fixup_f32 v155, v128, v155, 1.0
	v_div_scale_f32 v163, vcc, 1.0, v156, 1.0
	v_mul_f32_e32 v164, v163, v161
	v_div_scale_f32 v128, s[2:3], v157, v157, 1.0
	v_fma_f32 v162, -v160, v164, v163
	v_rcp_f32_e32 v129, v128
	v_fmac_f32_e32 v164, v162, v161
	s_nop 0
	v_fma_f32 v160, -v160, v164, v163
	v_fma_f32 v130, -v128, v129, 1.0
	v_div_fmas_f32 v160, v160, v161, v164
	v_fmac_f32_e32 v129, v130, v129
	v_div_fixup_f32 v156, v160, v156, 1.0
	v_div_scale_f32 v131, vcc, 1.0, v157, 1.0
	v_mul_f32_e32 v165, v131, v129
	v_div_scale_f32 v160, s[2:3], v158, v158, 1.0
	v_fma_f32 v130, -v128, v165, v131
	v_rcp_f32_e32 v161, v160
	v_fmac_f32_e32 v165, v130, v129
	s_nop 0
	v_fma_f32 v128, -v128, v165, v131
	v_fma_f32 v162, -v160, v161, 1.0
	v_div_fmas_f32 v128, v128, v129, v165
	v_fmac_f32_e32 v161, v162, v161
	v_div_fixup_f32 v157, v128, v157, 1.0
	v_div_scale_f32 v163, vcc, 1.0, v158, 1.0
	v_mul_f32_e32 v164, v163, v161
	v_div_scale_f32 v128, s[2:3], v159, v159, 1.0
	v_fma_f32 v162, -v160, v164, v163
	v_rcp_f32_e32 v129, v128
	v_fmac_f32_e32 v164, v162, v161
	s_nop 0
	v_fma_f32 v160, -v160, v164, v163
	v_fma_f32 v130, -v128, v129, 1.0
	v_div_fmas_f32 v160, v160, v161, v164
	v_fmac_f32_e32 v129, v130, v129
	v_div_fixup_f32 v158, v160, v158, 1.0
	v_div_scale_f32 v131, vcc, 1.0, v159, 1.0
	v_mul_f32_e32 v165, v131, v129
	v_fma_f32 v130, -v128, v165, v131
	v_fmac_f32_e32 v165, v130, v129
	v_fma_f32 v128, -v128, v165, v131
	v_div_fmas_f32 v128, v128, v129, v165
	v_div_fixup_f32 v159, v128, v159, 1.0
	v_pk_mul_f32 v[152:153], v[28:29], v[152:153]
	v_pk_mul_f32 v[154:155], v[30:31], v[154:155]
	v_pk_mul_f32 v[156:157], v[24:25], v[156:157]
	v_pk_mul_f32 v[158:159], v[26:27], v[158:159]
	v_cvt_pk_bf16_f32 v168, v152, v153
	v_cvt_pk_bf16_f32 v169, v154, v155
	v_cvt_pk_bf16_f32 v170, v156, v157
	v_cvt_pk_bf16_f32 v171, v158, v159
	global_store_dwordx4 v190, v[168:171], s[68:69]
	s_waitcnt vmcnt(5)
; __device__ __forceinline__ float sigmoidf_(float x) { return 1.f / (1.f + __expf(-x)); }
	v_lshlrev_b32_e32 v152, 16, v52
	v_and_b32_e32 v153, 0xffff0000, v52
	v_lshlrev_b32_e32 v154, 16, v53
	v_and_b32_e32 v155, 0xffff0000, v53
	v_lshlrev_b32_e32 v156, 16, v54
	v_and_b32_e32 v157, 0xffff0000, v54
	v_lshlrev_b32_e32 v158, 16, v55
	v_and_b32_e32 v159, 0xffff0000, v55
	v_mul_f32_e32 v152, 0xbfb8aa3b, v152
	v_mul_f32_e32 v153, 0xbfb8aa3b, v153
	v_mul_f32_e32 v154, 0xbfb8aa3b, v154
	v_mul_f32_e32 v155, 0xbfb8aa3b, v155
	v_mul_f32_e32 v156, 0xbfb8aa3b, v156
	v_mul_f32_e32 v157, 0xbfb8aa3b, v157
	v_mul_f32_e32 v158, 0xbfb8aa3b, v158
	v_mul_f32_e32 v159, 0xbfb8aa3b, v159
	v_exp_f32_e32 v152, v152
	v_exp_f32_e32 v153, v153
	v_exp_f32_e32 v154, v154
	v_exp_f32_e32 v155, v155
	v_exp_f32_e32 v156, v156
	v_exp_f32_e32 v157, v157
	v_exp_f32_e32 v158, v158
	v_exp_f32_e32 v159, v159
	v_pk_add_f32 v[152:153], v[152:153], 1.0 op_sel_hi:[1,0]
	v_pk_add_f32 v[154:155], v[154:155], 1.0 op_sel_hi:[1,0]
	v_pk_add_f32 v[156:157], v[156:157], 1.0 op_sel_hi:[1,0]
	v_pk_add_f32 v[158:159], v[158:159], 1.0 op_sel_hi:[1,0]
	v_div_scale_f32 v160, s[2:3], v152, v152, 1.0
	v_rcp_f32_e32 v161, v160
	s_nop 0
	v_fma_f32 v162, -v160, v161, 1.0
	v_fmac_f32_e32 v161, v162, v161
	v_div_scale_f32 v163, vcc, 1.0, v152, 1.0
	v_mul_f32_e32 v164, v163, v161
	v_div_scale_f32 v128, s[2:3], v153, v153, 1.0
	v_fma_f32 v162, -v160, v164, v163
	v_rcp_f32_e32 v129, v128
	v_fmac_f32_e32 v164, v162, v161
	s_nop 0
	v_fma_f32 v160, -v160, v164, v163
	v_fma_f32 v130, -v128, v129, 1.0
	v_div_fmas_f32 v160, v160, v161, v164
	v_fmac_f32_e32 v129, v130, v129
	v_div_fixup_f32 v152, v160, v152, 1.0
	v_div_scale_f32 v131, vcc, 1.0, v153, 1.0
	v_mul_f32_e32 v165, v131, v129
	v_div_scale_f32 v160, s[2:3], v154, v154, 1.0
	v_fma_f32 v130, -v128, v165, v131
	v_rcp_f32_e32 v161, v160
	v_fmac_f32_e32 v165, v130, v129
	s_nop 0
	v_fma_f32 v128, -v128, v165, v131
	v_fma_f32 v162, -v160, v161, 1.0
	v_div_fmas_f32 v128, v128, v129, v165
	v_fmac_f32_e32 v161, v162, v161
	v_div_fixup_f32 v153, v128, v153, 1.0
	v_div_scale_f32 v163, vcc, 1.0, v154, 1.0
	v_mul_f32_e32 v164, v163, v161
	v_div_scale_f32 v128, s[2:3], v155, v155, 1.0
	v_fma_f32 v162, -v160, v164, v163
	v_rcp_f32_e32 v129, v128
	v_fmac_f32_e32 v164, v162, v161
	s_nop 0
	v_fma_f32 v160, -v160, v164, v163
	v_fma_f32 v130, -v128, v129, 1.0
	v_div_fmas_f32 v160, v160, v161, v164
	v_fmac_f32_e32 v129, v130, v129
	v_div_fixup_f32 v154, v160, v154, 1.0
	v_div_scale_f32 v131, vcc, 1.0, v155, 1.0
	v_mul_f32_e32 v165, v131, v129
	v_div_scale_f32 v160, s[2:3], v156, v156, 1.0
	v_fma_f32 v130, -v128, v165, v131
	v_rcp_f32_e32 v161, v160
	v_fmac_f32_e32 v165, v130, v129
	s_nop 0
	v_fma_f32 v128, -v128, v165, v131
	v_fma_f32 v162, -v160, v161, 1.0
	v_div_fmas_f32 v128, v128, v129, v165
	v_fmac_f32_e32 v161, v162, v161
	v_div_fixup_f32 v155, v128, v155, 1.0
	v_div_scale_f32 v163, vcc, 1.0, v156, 1.0
	v_mul_f32_e32 v164, v163, v161
	v_div_scale_f32 v128, s[2:3], v157, v157, 1.0
	v_fma_f32 v162, -v160, v164, v163
	v_rcp_f32_e32 v129, v128
	v_fmac_f32_e32 v164, v162, v161
	s_nop 0
	v_fma_f32 v160, -v160, v164, v163
	v_fma_f32 v130, -v128, v129, 1.0
	v_div_fmas_f32 v160, v160, v161, v164
	v_fmac_f32_e32 v129, v130, v129
	v_div_fixup_f32 v156, v160, v156, 1.0
	v_div_scale_f32 v131, vcc, 1.0, v157, 1.0
	v_mul_f32_e32 v165, v131, v129
	v_div_scale_f32 v160, s[2:3], v158, v158, 1.0
	v_fma_f32 v130, -v128, v165, v131
	v_rcp_f32_e32 v161, v160
	v_fmac_f32_e32 v165, v130, v129
	s_nop 0
	v_fma_f32 v128, -v128, v165, v131
	v_fma_f32 v162, -v160, v161, 1.0
	v_div_fmas_f32 v128, v128, v129, v165
	v_fmac_f32_e32 v161, v162, v161
	v_div_fixup_f32 v157, v128, v157, 1.0
	v_div_scale_f32 v163, vcc, 1.0, v158, 1.0
	v_mul_f32_e32 v164, v163, v161
	v_div_scale_f32 v128, s[2:3], v159, v159, 1.0
	v_fma_f32 v162, -v160, v164, v163
	v_rcp_f32_e32 v129, v128
	v_fmac_f32_e32 v164, v162, v161
	s_nop 0
	v_fma_f32 v160, -v160, v164, v163
	v_fma_f32 v130, -v128, v129, 1.0
	v_div_fmas_f32 v160, v160, v161, v164
	v_fmac_f32_e32 v129, v130, v129
	v_div_fixup_f32 v158, v160, v158, 1.0
	v_div_scale_f32 v131, vcc, 1.0, v159, 1.0
	v_mul_f32_e32 v165, v131, v129
	v_fma_f32 v130, -v128, v165, v131
	v_fmac_f32_e32 v165, v130, v129
	v_fma_f32 v128, -v128, v165, v131
	v_div_fmas_f32 v128, v128, v129, v165
	v_div_fixup_f32 v159, v128, v159, 1.0
	v_pk_mul_f32 v[152:153], v[20:21], v[152:153]
	v_pk_mul_f32 v[154:155], v[22:23], v[154:155]
	v_pk_mul_f32 v[156:157], v[16:17], v[156:157]
	v_pk_mul_f32 v[158:159], v[18:19], v[158:159]
	v_cvt_pk_bf16_f32 v168, v152, v153
	v_cvt_pk_bf16_f32 v169, v154, v155
	v_cvt_pk_bf16_f32 v170, v156, v157
	v_cvt_pk_bf16_f32 v171, v158, v159
	global_store_dwordx4 v190, v[168:171], s[68:69] offset:256
	s_waitcnt vmcnt(4)
; __device__ __forceinline__ float sigmoidf_(float x) { return 1.f / (1.f + __expf(-x)); }
	v_lshlrev_b32_e32 v152, 16, v44
	v_and_b32_e32 v153, 0xffff0000, v44
	v_lshlrev_b32_e32 v154, 16, v45
	v_and_b32_e32 v155, 0xffff0000, v45
	v_lshlrev_b32_e32 v156, 16, v46
	v_and_b32_e32 v157, 0xffff0000, v46
	v_lshlrev_b32_e32 v158, 16, v47
	v_and_b32_e32 v159, 0xffff0000, v47
	v_mul_f32_e32 v152, 0xbfb8aa3b, v152
	v_mul_f32_e32 v153, 0xbfb8aa3b, v153
	v_mul_f32_e32 v154, 0xbfb8aa3b, v154
	v_mul_f32_e32 v155, 0xbfb8aa3b, v155
	v_mul_f32_e32 v156, 0xbfb8aa3b, v156
	v_mul_f32_e32 v157, 0xbfb8aa3b, v157
	v_mul_f32_e32 v158, 0xbfb8aa3b, v158
	v_mul_f32_e32 v159, 0xbfb8aa3b, v159
	v_exp_f32_e32 v152, v152
	v_exp_f32_e32 v153, v153
	v_exp_f32_e32 v154, v154
	v_exp_f32_e32 v155, v155
	v_exp_f32_e32 v156, v156
	v_exp_f32_e32 v157, v157
	v_exp_f32_e32 v158, v158
	v_exp_f32_e32 v159, v159
	v_pk_add_f32 v[152:153], v[152:153], 1.0 op_sel_hi:[1,0]
	v_pk_add_f32 v[154:155], v[154:155], 1.0 op_sel_hi:[1,0]
	v_pk_add_f32 v[156:157], v[156:157], 1.0 op_sel_hi:[1,0]
	v_pk_add_f32 v[158:159], v[158:159], 1.0 op_sel_hi:[1,0]
	v_div_scale_f32 v160, s[2:3], v152, v152, 1.0
	v_rcp_f32_e32 v161, v160
	s_nop 0
	v_fma_f32 v162, -v160, v161, 1.0
	v_fmac_f32_e32 v161, v162, v161
	v_div_scale_f32 v163, vcc, 1.0, v152, 1.0
	v_mul_f32_e32 v164, v163, v161
	v_div_scale_f32 v128, s[2:3], v153, v153, 1.0
	v_fma_f32 v162, -v160, v164, v163
	v_rcp_f32_e32 v129, v128
	v_fmac_f32_e32 v164, v162, v161
	s_nop 0
	v_fma_f32 v160, -v160, v164, v163
	v_fma_f32 v130, -v128, v129, 1.0
	v_div_fmas_f32 v160, v160, v161, v164
	v_fmac_f32_e32 v129, v130, v129
	v_div_fixup_f32 v152, v160, v152, 1.0
	v_div_scale_f32 v131, vcc, 1.0, v153, 1.0
	v_mul_f32_e32 v165, v131, v129
	v_div_scale_f32 v160, s[2:3], v154, v154, 1.0
	v_fma_f32 v130, -v128, v165, v131
	v_rcp_f32_e32 v161, v160
	v_fmac_f32_e32 v165, v130, v129
	s_nop 0
	v_fma_f32 v128, -v128, v165, v131
	v_fma_f32 v162, -v160, v161, 1.0
	v_div_fmas_f32 v128, v128, v129, v165
	v_fmac_f32_e32 v161, v162, v161
	v_div_fixup_f32 v153, v128, v153, 1.0
	v_div_scale_f32 v163, vcc, 1.0, v154, 1.0
	v_mul_f32_e32 v164, v163, v161
	v_div_scale_f32 v128, s[2:3], v155, v155, 1.0
	v_fma_f32 v162, -v160, v164, v163
	v_rcp_f32_e32 v129, v128
	v_fmac_f32_e32 v164, v162, v161
	s_nop 0
	v_fma_f32 v160, -v160, v164, v163
	v_fma_f32 v130, -v128, v129, 1.0
	v_div_fmas_f32 v160, v160, v161, v164
	v_fmac_f32_e32 v129, v130, v129
	v_div_fixup_f32 v154, v160, v154, 1.0
	v_div_scale_f32 v131, vcc, 1.0, v155, 1.0
	v_mul_f32_e32 v165, v131, v129
	v_div_scale_f32 v160, s[2:3], v156, v156, 1.0
	v_fma_f32 v130, -v128, v165, v131
	v_rcp_f32_e32 v161, v160
	v_fmac_f32_e32 v165, v130, v129
	s_nop 0
	v_fma_f32 v128, -v128, v165, v131
	v_fma_f32 v162, -v160, v161, 1.0
	v_div_fmas_f32 v128, v128, v129, v165
	v_fmac_f32_e32 v161, v162, v161
	v_div_fixup_f32 v155, v128, v155, 1.0
	v_div_scale_f32 v163, vcc, 1.0, v156, 1.0
	v_mul_f32_e32 v164, v163, v161
	v_div_scale_f32 v128, s[2:3], v157, v157, 1.0
	v_fma_f32 v162, -v160, v164, v163
	v_rcp_f32_e32 v129, v128
	v_fmac_f32_e32 v164, v162, v161
	s_nop 0
	v_fma_f32 v160, -v160, v164, v163
	v_fma_f32 v130, -v128, v129, 1.0
	v_div_fmas_f32 v160, v160, v161, v164
	v_fmac_f32_e32 v129, v130, v129
	v_div_fixup_f32 v156, v160, v156, 1.0
	v_div_scale_f32 v131, vcc, 1.0, v157, 1.0
	v_mul_f32_e32 v165, v131, v129
	v_div_scale_f32 v160, s[2:3], v158, v158, 1.0
	v_fma_f32 v130, -v128, v165, v131
	v_rcp_f32_e32 v161, v160
	v_fmac_f32_e32 v165, v130, v129
	s_nop 0
	v_fma_f32 v128, -v128, v165, v131
	v_fma_f32 v162, -v160, v161, 1.0
	v_div_fmas_f32 v128, v128, v129, v165
	v_fmac_f32_e32 v161, v162, v161
	v_div_fixup_f32 v157, v128, v157, 1.0
	v_div_scale_f32 v163, vcc, 1.0, v158, 1.0
	v_mul_f32_e32 v164, v163, v161
	v_div_scale_f32 v128, s[2:3], v159, v159, 1.0
	v_fma_f32 v162, -v160, v164, v163
	v_rcp_f32_e32 v129, v128
	v_fmac_f32_e32 v164, v162, v161
	s_nop 0
	v_fma_f32 v160, -v160, v164, v163
	v_fma_f32 v130, -v128, v129, 1.0
	v_div_fmas_f32 v160, v160, v161, v164
	v_fmac_f32_e32 v129, v130, v129
	v_div_fixup_f32 v158, v160, v158, 1.0
	v_div_scale_f32 v131, vcc, 1.0, v159, 1.0
	v_mul_f32_e32 v165, v131, v129
	v_fma_f32 v130, -v128, v165, v131
	v_fmac_f32_e32 v165, v130, v129
	v_fma_f32 v128, -v128, v165, v131
	v_div_fmas_f32 v128, v128, v129, v165
	v_div_fixup_f32 v159, v128, v159, 1.0
	v_pk_mul_f32 v[152:153], v[12:13], v[152:153]
	v_pk_mul_f32 v[154:155], v[14:15], v[154:155]
	v_pk_mul_f32 v[156:157], v[8:9], v[156:157]
	v_pk_mul_f32 v[158:159], v[10:11], v[158:159]
	v_cvt_pk_bf16_f32 v168, v152, v153
	v_cvt_pk_bf16_f32 v169, v154, v155
	v_cvt_pk_bf16_f32 v170, v156, v157
	v_cvt_pk_bf16_f32 v171, v158, v159
	global_store_dwordx4 v191, v[168:171], s[68:69]
	s_waitcnt vmcnt(3)
; __device__ __forceinline__ float sigmoidf_(float x) { return 1.f / (1.f + __expf(-x)); }
	v_lshlrev_b32_e32 v152, 16, v36
	v_and_b32_e32 v153, 0xffff0000, v36
	v_lshlrev_b32_e32 v154, 16, v37
	v_and_b32_e32 v155, 0xffff0000, v37
	v_lshlrev_b32_e32 v156, 16, v38
	v_and_b32_e32 v157, 0xffff0000, v38
	v_lshlrev_b32_e32 v158, 16, v39
	v_and_b32_e32 v159, 0xffff0000, v39
	v_mul_f32_e32 v152, 0xbfb8aa3b, v152
	v_mul_f32_e32 v153, 0xbfb8aa3b, v153
	v_mul_f32_e32 v154, 0xbfb8aa3b, v154
	v_mul_f32_e32 v155, 0xbfb8aa3b, v155
	v_mul_f32_e32 v156, 0xbfb8aa3b, v156
	v_mul_f32_e32 v157, 0xbfb8aa3b, v157
	v_mul_f32_e32 v158, 0xbfb8aa3b, v158
	v_mul_f32_e32 v159, 0xbfb8aa3b, v159
	v_exp_f32_e32 v152, v152
	v_exp_f32_e32 v153, v153
	v_exp_f32_e32 v154, v154
	v_exp_f32_e32 v155, v155
	v_exp_f32_e32 v156, v156
	v_exp_f32_e32 v157, v157
	v_exp_f32_e32 v158, v158
	v_exp_f32_e32 v159, v159
	v_pk_add_f32 v[152:153], v[152:153], 1.0 op_sel_hi:[1,0]
	v_pk_add_f32 v[154:155], v[154:155], 1.0 op_sel_hi:[1,0]
	v_pk_add_f32 v[156:157], v[156:157], 1.0 op_sel_hi:[1,0]
	v_pk_add_f32 v[158:159], v[158:159], 1.0 op_sel_hi:[1,0]
	v_div_scale_f32 v160, s[2:3], v152, v152, 1.0
	v_rcp_f32_e32 v161, v160
	s_nop 0
	v_fma_f32 v162, -v160, v161, 1.0
	v_fmac_f32_e32 v161, v162, v161
	v_div_scale_f32 v163, vcc, 1.0, v152, 1.0
	v_mul_f32_e32 v164, v163, v161
	v_div_scale_f32 v128, s[2:3], v153, v153, 1.0
	v_fma_f32 v162, -v160, v164, v163
	v_rcp_f32_e32 v129, v128
	v_fmac_f32_e32 v164, v162, v161
	s_nop 0
	v_fma_f32 v160, -v160, v164, v163
	v_fma_f32 v130, -v128, v129, 1.0
	v_div_fmas_f32 v160, v160, v161, v164
	v_fmac_f32_e32 v129, v130, v129
	v_div_fixup_f32 v152, v160, v152, 1.0
	v_div_scale_f32 v131, vcc, 1.0, v153, 1.0
	v_mul_f32_e32 v165, v131, v129
	v_div_scale_f32 v160, s[2:3], v154, v154, 1.0
	v_fma_f32 v130, -v128, v165, v131
	v_rcp_f32_e32 v161, v160
	v_fmac_f32_e32 v165, v130, v129
	s_nop 0
	v_fma_f32 v128, -v128, v165, v131
	v_fma_f32 v162, -v160, v161, 1.0
	v_div_fmas_f32 v128, v128, v129, v165
	v_fmac_f32_e32 v161, v162, v161
	v_div_fixup_f32 v153, v128, v153, 1.0
	v_div_scale_f32 v163, vcc, 1.0, v154, 1.0
	v_mul_f32_e32 v164, v163, v161
	v_div_scale_f32 v128, s[2:3], v155, v155, 1.0
	v_fma_f32 v162, -v160, v164, v163
	v_rcp_f32_e32 v129, v128
	v_fmac_f32_e32 v164, v162, v161
	s_nop 0
	v_fma_f32 v160, -v160, v164, v163
	v_fma_f32 v130, -v128, v129, 1.0
	v_div_fmas_f32 v160, v160, v161, v164
	v_fmac_f32_e32 v129, v130, v129
	v_div_fixup_f32 v154, v160, v154, 1.0
	v_div_scale_f32 v131, vcc, 1.0, v155, 1.0
	v_mul_f32_e32 v165, v131, v129
	v_div_scale_f32 v160, s[2:3], v156, v156, 1.0
	v_fma_f32 v130, -v128, v165, v131
	v_rcp_f32_e32 v161, v160
	v_fmac_f32_e32 v165, v130, v129
	s_nop 0
	v_fma_f32 v128, -v128, v165, v131
	v_fma_f32 v162, -v160, v161, 1.0
	v_div_fmas_f32 v128, v128, v129, v165
	v_fmac_f32_e32 v161, v162, v161
	v_div_fixup_f32 v155, v128, v155, 1.0
	v_div_scale_f32 v163, vcc, 1.0, v156, 1.0
	v_mul_f32_e32 v164, v163, v161
	v_div_scale_f32 v128, s[2:3], v157, v157, 1.0
	v_fma_f32 v162, -v160, v164, v163
	v_rcp_f32_e32 v129, v128
	v_fmac_f32_e32 v164, v162, v161
	s_nop 0
	v_fma_f32 v160, -v160, v164, v163
	v_fma_f32 v130, -v128, v129, 1.0
	v_div_fmas_f32 v160, v160, v161, v164
	v_fmac_f32_e32 v129, v130, v129
	v_div_fixup_f32 v156, v160, v156, 1.0
	v_div_scale_f32 v131, vcc, 1.0, v157, 1.0
	v_mul_f32_e32 v165, v131, v129
	v_div_scale_f32 v160, s[2:3], v158, v158, 1.0
	v_fma_f32 v130, -v128, v165, v131
	v_rcp_f32_e32 v161, v160
	v_fmac_f32_e32 v165, v130, v129
	s_nop 0
	v_fma_f32 v128, -v128, v165, v131
	v_fma_f32 v162, -v160, v161, 1.0
	v_div_fmas_f32 v128, v128, v129, v165
	v_fmac_f32_e32 v161, v162, v161
	v_div_fixup_f32 v157, v128, v157, 1.0
	v_div_scale_f32 v163, vcc, 1.0, v158, 1.0
	v_mul_f32_e32 v164, v163, v161
	v_div_scale_f32 v128, s[2:3], v159, v159, 1.0
	v_fma_f32 v162, -v160, v164, v163
	v_rcp_f32_e32 v129, v128
	v_fmac_f32_e32 v164, v162, v161
	s_nop 0
	v_fma_f32 v160, -v160, v164, v163
	v_fma_f32 v130, -v128, v129, 1.0
	v_div_fmas_f32 v160, v160, v161, v164
	v_fmac_f32_e32 v129, v130, v129
	v_div_fixup_f32 v158, v160, v158, 1.0
	v_div_scale_f32 v131, vcc, 1.0, v159, 1.0
	v_mul_f32_e32 v165, v131, v129
	v_fma_f32 v130, -v128, v165, v131
	v_fmac_f32_e32 v165, v130, v129
	v_fma_f32 v128, -v128, v165, v131
	v_div_fmas_f32 v128, v128, v129, v165
	v_div_fixup_f32 v159, v128, v159, 1.0
	v_pk_mul_f32 v[152:153], v[4:5], v[152:153]
	v_pk_mul_f32 v[154:155], v[6:7], v[154:155]
	v_pk_mul_f32 v[156:157], v[0:1], v[156:157]
	v_pk_mul_f32 v[158:159], v[2:3], v[158:159]
	v_cvt_pk_bf16_f32 v168, v152, v153
	v_cvt_pk_bf16_f32 v169, v154, v155
	v_cvt_pk_bf16_f32 v170, v156, v157
	v_cvt_pk_bf16_f32 v171, v158, v159
	global_store_dwordx4 v191, v[168:171], s[68:69] offset:256
	s_branch .LBB0_567
